# mixb: the 80 relative-bias LDS lookups issued up front into spare registers (one pipelined burst instead of 80 dependent ds_read + lgkmcnt(0) round trips inside the masked blocks)
# speedup vs baseline: 1.0241x; 1.0000x over previous
; DI f32x16 mfma(bf16x8 a, bf16x8 b, f32x16 c) { return __builtin_amdgcn_mfma_f32_32x32x16_bf16(a, b, c, 0, 0, 0); }
; DI f32x16 zero16() { f32x16 z; for (int i = 0; i < 16; ++i) z[i] = 0.f; return z; }
; DI void phase_mixb(const Prm& p, unsigned char* smem_raw, int S, int lgS, int& base) {
;     ...
;     const int wt = t * 8 + wave;
;     const int hg = wt & 1, g = (wt >> 1) % 3, blk = wt / 6;
;     const int seq = blk >> (lgS - 5), b_in = blk & ((S >> 5) - 1);
;     const int lgd = 2 * g, L = S >> lgd;
;     const int lgbpr = lgS - lgd - 5;
;     const int res = b_in >> lgbpr, i0 = (b_in & ((1 << lgbpr) - 1)) << 5;
;     const int tokbase = seq * S + res;
;     const int hd = g * 2 + hg, hc = hd * 64;
;     const int qi = i0 + lr;
;     const int qtok = tokbase + (qi << lgd);
;     bf16x8 qf[4];
; #pragma unroll
;     for (int ks = 0; ks < 4; ++ks) qf[ks] = *(const bf16x8*)(p.bqkv + (size_t)qtok * 1152 + hc + ks * 16 + lh * 8);
;     f32x16 sc[5];
; #pragma unroll
;     for (int tt = 0; tt < 5; ++tt) {
;       int ik = i0 - 64 + 32 * tt + lr;
;       ik = min(max(ik, 0), L - 1);
;       const u16* kp = p.bqkv + (size_t)(tokbase + (ik << lgd)) * 1152 + 384 + hc + lh * 8;
;       sc[tt] = zero16();
; #pragma unroll
;       for (int ks = 0; ks < 4; ++ks) sc[tt] = mfma(*(const bf16x8*)(kp + ks * 16), qf[ks], sc[tt]);
;     }
.LBB0_1837:
	v_ashrrev_i32_e32 v2, 1, v128
	s_mov_b32 s2, 0x55555556
	v_mul_hi_i32 v3, v2, s2
	v_lshrrev_b32_e32 v4, 31, v3
	v_add_u32_e32 v3, v3, v4
	v_lshl_add_u32 v3, v3, 1, v3
	v_sub_u32_e32 v2, v2, v3
	v_mul_hi_i32 v3, v128, s82
	v_lshrrev_b32_e32 v4, 31, v3
	v_add_u32_e32 v3, v3, v4
	v_readlane_b32 s2, v254, 48
	v_lshlrev_b32_e32 v99, 1, v2
	v_or_b32_e32 v98, v99, v104
	v_ashrrev_i32_e32 v4, s2, v3
	v_readlane_b32 s2, v254, 50
	v_readlane_b32 s36, v253, 24
	v_lshlrev_b32_e32 v100, 6, v98
	v_and_b32_e32 v3, s2, v3
	v_readlane_b32 s2, v254, 51
	v_readlane_b32 s38, v253, 26
	v_readlane_b32 s39, v253, 27
	v_sub_u32_e32 v2, s2, v99
	v_add_u32_e32 v2, -5, v2
	s_waitcnt vmcnt(9)
	v_bfe_u32 v135, v3, 0, v2
	v_lshrrev_b32_e32 v5, v2, v3
	v_lshlrev_b32_e32 v133, 5, v135
	v_lshl_add_u32 v131, v4, s2, v5
	v_or_b32_e32 v97, v133, v95
	v_lshl_add_u32 v130, v97, v99, v131
	v_mov_b64_e32 v[6:7], s[38:39]
	s_movk_i32 s4, 0x900
	v_ashrrev_i32_e32 v101, 31, v100
	v_mad_i64_i32 v[2:3], s[2:3], v130, s4, v[6:7]
	v_lshlrev_b64 v[102:103], 1, v[100:101]
	v_lshl_add_u64 v[2:3], v[2:3], 0, v[102:103]
	v_readlane_b32 s2, v254, 49
	v_lshl_add_u64 v[8:9], v[2:3], 0, v[0:1]
	v_add_u32_e32 v14, v133, v105
	v_lshrrev_b32_e64 v134, v99, s2
	global_load_dwordx4 v[2:5], v[8:9], off
	global_load_dwordx4 v[90:93], v[8:9], off offset:32
	global_load_dwordx4 v[86:89], v[8:9], off offset:64
	global_load_dwordx4 v[82:85], v[8:9], off offset:96
	v_add_u32_e32 v132, -1, v134
	v_max_i32_e32 v8, 0, v14
	v_min_i32_e32 v8, v8, v132
	v_lshl_add_u32 v8, v8, v99, v131
	v_mad_i64_i32 v[8:9], s[2:3], v8, s4, v[6:7]
	v_lshl_add_u64 v[8:9], v[8:9], 0, v[102:103]
	v_lshl_add_u64 v[12:13], v[8:9], 0, v[0:1]
	global_load_dwordx4 v[144:147], v[12:13], off offset:768
	global_load_dwordx4 v[148:151], v[12:13], off offset:800
	global_load_dwordx4 v[152:155], v[12:13], off offset:832
	global_load_dwordx4 v[156:159], v[12:13], off offset:864
	v_max_i32_e32 v8, 0xffffffe0, v14
	v_add_u32_e32 v8, 32, v8
	v_min_i32_e32 v8, v8, v132
	v_lshl_add_u32 v8, v8, v99, v131
	v_mad_i64_i32 v[8:9], s[2:3], v8, s4, v[6:7]
	v_lshl_add_u64 v[8:9], v[8:9], 0, v[102:103]
	v_lshl_add_u64 v[136:137], v[8:9], 0, v[0:1]
	global_load_dwordx4 v[160:163], v[136:137], off offset:768
	global_load_dwordx4 v[164:167], v[136:137], off offset:800
	global_load_dwordx4 v[168:171], v[136:137], off offset:832
	global_load_dwordx4 v[172:175], v[136:137], off offset:864
	v_max_i32_e32 v8, 0xffffffc0, v14
	v_add_u32_e32 v8, 64, v8
	v_min_i32_e32 v8, v8, v132
	v_lshl_add_u32 v8, v8, v99, v131
	v_mad_i64_i32 v[8:9], s[2:3], v8, s4, v[6:7]
	v_lshl_add_u64 v[8:9], v[8:9], 0, v[102:103]
	v_lshl_add_u64 v[138:139], v[8:9], 0, v[0:1]
	global_load_dwordx4 v[176:179], v[138:139], off offset:768
	global_load_dwordx4 v[180:183], v[138:139], off offset:800
	global_load_dwordx4 v[184:187], v[138:139], off offset:832
	global_load_dwordx4 v[188:191], v[138:139], off offset:864
	v_max_i32_e32 v8, 0xffffffa0, v14
	v_add_u32_e32 v8, 0x60, v8
	v_min_i32_e32 v8, v8, v132
	v_lshl_add_u32 v8, v8, v99, v131
	v_mad_i64_i32 v[8:9], s[2:3], v8, s4, v[6:7]
	v_lshl_add_u64 v[8:9], v[8:9], 0, v[102:103]
	v_lshl_add_u64 v[140:141], v[8:9], 0, v[0:1]
	global_load_dwordx4 v[192:195], v[140:141], off offset:768
	global_load_dwordx4 v[196:199], v[140:141], off offset:800
	global_load_dwordx4 v[200:203], v[140:141], off offset:832
	global_load_dwordx4 v[204:207], v[140:141], off offset:864
	v_max_i32_e32 v8, 0xffffff80, v14
	v_add_u32_e32 v8, 0x80, v8
	v_min_i32_e32 v8, v8, v132
	v_lshl_add_u32 v8, v8, v99, v131
	v_mad_i64_i32 v[8:9], s[2:3], v8, s4, v[6:7]
	v_lshl_add_u64 v[8:9], v[8:9], 0, v[102:103]
	v_lshl_add_u64 v[142:143], v[8:9], 0, v[0:1]
	global_load_dwordx4 v[208:211], v[142:143], off offset:768
	global_load_dwordx4 v[212:215], v[142:143], off offset:800
	global_load_dwordx4 v[216:219], v[142:143], off offset:832
	global_load_dwordx4 v[220:223], v[142:143], off offset:864
	v_cmp_lt_u32_e32 vcc, 1, v135
	v_readlane_b32 s37, v253, 25
	v_readlane_b32 s40, v253, 28
	v_readlane_b32 s41, v253, 29
	v_readlane_b32 s42, v253, 30
	v_readlane_b32 s43, v253, 31
	v_readlane_b32 s44, v253, 32
	v_readlane_b32 s45, v253, 33
	v_readlane_b32 s46, v253, 34
	v_readlane_b32 s47, v253, 35
	v_readlane_b32 s48, v253, 36
	v_readlane_b32 s49, v253, 37
	v_readlane_b32 s50, v253, 38
	v_readlane_b32 s51, v253, 39
	s_waitcnt vmcnt(16)
	v_mfma_f32_32x32x16_bf16 v[66:81], v[144:147], v[2:5], 0
	v_mfma_f32_32x32x16_bf16 v[66:81], v[148:151], v[90:93], v[66:81]
	v_mfma_f32_32x32x16_bf16 v[66:81], v[152:155], v[86:89], v[66:81]
	v_mfma_f32_32x32x16_bf16 v[66:81], v[156:159], v[82:85], v[66:81]
	s_waitcnt vmcnt(12)
	v_mfma_f32_32x32x16_bf16 v[50:65], v[160:163], v[2:5], 0
	v_mfma_f32_32x32x16_bf16 v[50:65], v[164:167], v[90:93], v[50:65]
	v_mfma_f32_32x32x16_bf16 v[50:65], v[168:171], v[86:89], v[50:65]
	v_mfma_f32_32x32x16_bf16 v[50:65], v[172:175], v[82:85], v[50:65]
	s_waitcnt vmcnt(8)
	v_mfma_f32_32x32x16_bf16 v[34:49], v[176:179], v[2:5], 0
	v_mfma_f32_32x32x16_bf16 v[34:49], v[180:183], v[90:93], v[34:49]
	v_mfma_f32_32x32x16_bf16 v[34:49], v[184:187], v[86:89], v[34:49]
	v_mfma_f32_32x32x16_bf16 v[34:49], v[188:191], v[82:85], v[34:49]
	s_waitcnt vmcnt(4)
	v_mfma_f32_32x32x16_bf16 v[18:33], v[192:195], v[2:5], 0
	v_mfma_f32_32x32x16_bf16 v[18:33], v[196:199], v[90:93], v[18:33]
	v_mfma_f32_32x32x16_bf16 v[18:33], v[200:203], v[86:89], v[18:33]
	v_mfma_f32_32x32x16_bf16 v[18:33], v[204:207], v[82:85], v[18:33]
	s_waitcnt vmcnt(0)
; DI int rowmap(int r, int lh) { return (r & 3) + 8 * (r >> 2) + 4 * lh; }
; DI void phase_mixb(const Prm& p, unsigned char* smem_raw, int S, int lgS, int& base) {
;     ...
;     float mx = -1e30f;
; #pragma unroll
;     for (int tt = 0; tt < 5; ++tt)
; #pragma unroll
;       for (int r = 0; r < 16; ++r) {
;         const int ik = i0 - 64 + 32 * tt + rowmap(r, lh);
;         const int rel = ik - qi;
;         const bool valid = (rel >= -64) && (rel <= 64) && (ik >= 0) && (ik < L);
;         const int bi = min(max(rel + 64, 0), 128);
;         const float s = valid ? (sc[tt][r] * 0.125f + bt[hd * 129 + bi]) * LOG2E : -1e30f;
;         sc[tt][r] = s;
;         mx = fmaxf(mx, s);
;       }
	v_mfma_f32_32x32x16_bf16 v[2:17], v[208:211], v[2:5], 0
	v_mfma_f32_32x32x16_bf16 v[2:17], v[212:215], v[90:93], v[2:17]
	v_mfma_f32_32x32x16_bf16 v[2:17], v[216:219], v[86:89], v[2:17]
	v_mfma_f32_32x32x16_bf16 v[2:17], v[220:223], v[82:85], v[2:17]
	v_subrev_u32_e32 v82, 64, v133
	v_or_b32_e32 v86, v82, v94
	v_sub_u32_e32 v83, v86, v97
	v_add_u32_e32 v84, 64, v83
	v_mul_i32_i24_e32 v87, 0x204, v98
	v_lshl_add_u32 v85, v84, 2, v87
	ds_read_b32 v148, v85
	v_or_b32_e32 v82, 1, v86
	v_sub_u32_e32 v83, v82, v97
	v_add_u32_e32 v84, 64, v83
	v_lshl_add_u32 v85, v84, 2, v87
	ds_read_b32 v149, v85
	v_or_b32_e32 v82, 2, v86
	v_sub_u32_e32 v83, v82, v97
	v_add_u32_e32 v84, 64, v83
	v_lshl_add_u32 v85, v84, 2, v87
	ds_read_b32 v150, v85
	v_or_b32_e32 v82, 3, v86
	v_sub_u32_e32 v83, v82, v97
	v_add_u32_e32 v84, 64, v83
	v_lshl_add_u32 v85, v84, 2, v87
	ds_read_b32 v151, v85
	v_or_b32_e32 v82, 8, v86
	v_sub_u32_e32 v83, v82, v97
	v_add_u32_e32 v84, 64, v83
	v_lshl_add_u32 v85, v84, 2, v87
	ds_read_b32 v152, v85
	v_or_b32_e32 v82, 9, v86
	v_sub_u32_e32 v83, v82, v97
	v_add_u32_e32 v84, 64, v83
	v_lshl_add_u32 v85, v84, 2, v87
	ds_read_b32 v153, v85
	v_or_b32_e32 v82, 10, v86
	v_sub_u32_e32 v83, v82, v97
	v_add_u32_e32 v84, 64, v83
	v_lshl_add_u32 v85, v84, 2, v87
	ds_read_b32 v154, v85
	v_or_b32_e32 v82, 11, v86
	v_sub_u32_e32 v83, v82, v97
	v_add_u32_e32 v84, 64, v83
	v_lshl_add_u32 v85, v84, 2, v87
	ds_read_b32 v155, v85
	s_waitcnt lgkmcnt(7)
	v_or_b32_e32 v82, 16, v86
	v_sub_u32_e32 v83, v82, v97
	v_add_u32_e32 v84, 64, v83
	v_lshl_add_u32 v85, v84, 2, v87
	ds_read_b32 v163, v85
	v_or_b32_e32 v82, 17, v86
	v_sub_u32_e32 v83, v82, v97
	v_add_u32_e32 v84, 64, v83
	v_lshl_add_u32 v85, v84, 2, v87
	ds_read_b32 v164, v85
	v_or_b32_e32 v82, 18, v86
	v_sub_u32_e32 v83, v82, v97
	v_add_u32_e32 v84, 64, v83
	v_lshl_add_u32 v85, v84, 2, v87
	ds_read_b32 v165, v85
	v_or_b32_e32 v82, 19, v86
	v_sub_u32_e32 v83, v82, v97
	v_add_u32_e32 v84, 64, v83
	v_lshl_add_u32 v85, v84, 2, v87
	ds_read_b32 v166, v85
	v_or_b32_e32 v82, 24, v86
	v_sub_u32_e32 v83, v82, v97
	v_add_u32_e32 v84, 64, v83
	v_lshl_add_u32 v85, v84, 2, v87
	ds_read_b32 v167, v85
	v_or_b32_e32 v82, 25, v86
	v_sub_u32_e32 v83, v82, v97
	v_add_u32_e32 v84, 64, v83
	v_lshl_add_u32 v85, v84, 2, v87
	ds_read_b32 v168, v85
	v_or_b32_e32 v82, 26, v86
	v_sub_u32_e32 v83, v82, v97
	v_add_u32_e32 v84, 64, v83
	v_lshl_add_u32 v85, v84, 2, v87
	ds_read_b32 v169, v85
	v_or_b32_e32 v82, 27, v86
	v_sub_u32_e32 v83, v82, v97
	v_add_u32_e32 v84, 64, v83
	v_lshl_add_u32 v85, v84, 2, v87
	ds_read_b32 v170, v85
	s_waitcnt lgkmcnt(7)
	v_subrev_u32_e32 v82, 32, v133
	v_or_b32_e32 v88, v82, v94
	v_sub_u32_e32 v83, v88, v97
	v_add_u32_e32 v84, 64, v83
	v_lshl_add_u32 v85, v84, 2, v87
	ds_read_b32 v171, v85
	v_or_b32_e32 v82, 1, v88
	v_sub_u32_e32 v83, v82, v97
	v_add_u32_e32 v84, 64, v83
	v_lshl_add_u32 v85, v84, 2, v87
	ds_read_b32 v172, v85
	v_or_b32_e32 v82, 2, v88
	v_sub_u32_e32 v83, v82, v97
	v_add_u32_e32 v84, 64, v83
	v_lshl_add_u32 v85, v84, 2, v87
	ds_read_b32 v173, v85
	v_or_b32_e32 v82, 3, v88
	v_sub_u32_e32 v83, v82, v97
	v_add_u32_e32 v84, 64, v83
	v_lshl_add_u32 v85, v84, 2, v87
	ds_read_b32 v174, v85
	v_or_b32_e32 v82, 8, v88
	v_sub_u32_e32 v83, v82, v97
	v_add_u32_e32 v84, 64, v83
	v_lshl_add_u32 v85, v84, 2, v87
	ds_read_b32 v175, v85
	v_or_b32_e32 v82, 9, v88
	v_sub_u32_e32 v83, v82, v97
	v_add_u32_e32 v84, 64, v83
	v_lshl_add_u32 v85, v84, 2, v87
	ds_read_b32 v176, v85
	v_or_b32_e32 v82, 10, v88
	v_sub_u32_e32 v83, v82, v97
	v_add_u32_e32 v84, 64, v83
	v_lshl_add_u32 v85, v84, 2, v87
	ds_read_b32 v177, v85
	v_or_b32_e32 v82, 11, v88
	v_sub_u32_e32 v83, v82, v97
	v_add_u32_e32 v84, 64, v83
	v_lshl_add_u32 v85, v84, 2, v87
	ds_read_b32 v178, v85
	s_waitcnt lgkmcnt(7)
	v_or_b32_e32 v82, 16, v88
	v_sub_u32_e32 v83, v82, v97
	v_add_u32_e32 v84, 64, v83
	v_lshl_add_u32 v85, v84, 2, v87
	ds_read_b32 v179, v85
	v_or_b32_e32 v82, 17, v88
	v_sub_u32_e32 v83, v82, v97
	v_add_u32_e32 v84, 64, v83
	v_lshl_add_u32 v85, v84, 2, v87
	ds_read_b32 v180, v85
	v_or_b32_e32 v82, 18, v88
	v_sub_u32_e32 v83, v82, v97
	v_add_u32_e32 v84, 64, v83
	v_lshl_add_u32 v85, v84, 2, v87
	ds_read_b32 v181, v85
	v_or_b32_e32 v82, 19, v88
	v_sub_u32_e32 v83, v82, v97
	v_add_u32_e32 v84, 64, v83
	v_lshl_add_u32 v85, v84, 2, v87
	ds_read_b32 v182, v85
	v_or_b32_e32 v82, 24, v88
	v_sub_u32_e32 v83, v82, v97
	v_add_u32_e32 v84, 64, v83
	v_lshl_add_u32 v85, v84, 2, v87
	ds_read_b32 v183, v85
	v_or_b32_e32 v82, 25, v88
	v_sub_u32_e32 v83, v82, v97
	v_add_u32_e32 v84, 64, v83
	v_lshl_add_u32 v85, v84, 2, v87
	ds_read_b32 v184, v85
	v_or_b32_e32 v82, 26, v88
	v_sub_u32_e32 v83, v82, v97
	v_add_u32_e32 v84, 64, v83
	v_lshl_add_u32 v85, v84, 2, v87
	ds_read_b32 v185, v85
	v_or_b32_e32 v82, 27, v88
	v_sub_u32_e32 v83, v82, v97
	v_add_u32_e32 v84, 64, v83
	v_lshl_add_u32 v85, v84, 2, v87
	ds_read_b32 v186, v85
	s_waitcnt lgkmcnt(7)
	v_lshl_add_u32 v82, v107, 2, v87
	ds_read_b32 v187, v82 offset:256
	v_or_b32_e32 v83, v133, v94
	v_sub_u32_e32 v84, v83, v97
	v_lshl_add_u32 v89, v84, 2, v87
	ds_read_b32 v188, v89 offset:260
	ds_read_b32 v189, v89 offset:264
	ds_read_b32 v190, v89 offset:268
	ds_read_b32 v191, v89 offset:288
	ds_read_b32 v192, v89 offset:292
	ds_read_b32 v193, v89 offset:296
	ds_read_b32 v194, v89 offset:300
	s_waitcnt lgkmcnt(7)
	ds_read_b32 v195, v89 offset:320
	ds_read_b32 v196, v89 offset:324
	ds_read_b32 v197, v89 offset:328
	ds_read_b32 v198, v89 offset:332
	ds_read_b32 v199, v89 offset:352
	ds_read_b32 v200, v89 offset:356
	ds_read_b32 v201, v89 offset:360
	ds_read_b32 v202, v89 offset:364
	s_waitcnt lgkmcnt(7)
; DI int rowmap(int r, int lh) { return (r & 3) + 8 * (r >> 2) + 4 * lh; }
; DI void phase_mixb(const Prm& p, unsigned char* smem_raw, int S, int lgS, int& base) {
;     ...
;     float mx = -1e30f;
; #pragma unroll
;     for (int tt = 0; tt < 5; ++tt)
; #pragma unroll
;       for (int r = 0; r < 16; ++r) {
;         const int ik = i0 - 64 + 32 * tt + rowmap(r, lh);
;         const int rel = ik - qi;
;         const bool valid = (rel >= -64) && (rel <= 64) && (ik >= 0) && (ik < L);
;         const int bi = min(max(rel + 64, 0), 128);
;         const float s = valid ? (sc[tt][r] * 0.125f + bt[hd * 129 + bi]) * LOG2E : -1e30f;
;         sc[tt][r] = s;
;         mx = fmaxf(mx, s);
;       }
	v_add_u32_e32 v85, v133, v94
	v_sub_u32_e32 v82, v85, v97
	v_lshl_add_u32 v83, v82, 2, v87
	ds_read_b32 v203, v83 offset:384
	v_add_u32_e32 v84, v133, v113
	v_sub_u32_e32 v85, v84, v97
	v_lshl_add_u32 v82, v85, 2, v87
	ds_read_b32 v204, v82 offset:384
	v_add_u32_e32 v83, v133, v114
	v_sub_u32_e32 v84, v83, v97
	v_lshl_add_u32 v85, v84, 2, v87
	ds_read_b32 v205, v85 offset:384
	v_add_u32_e32 v82, v133, v115
	v_sub_u32_e32 v83, v82, v97
	v_lshl_add_u32 v84, v83, 2, v87
	ds_read_b32 v206, v84 offset:384
	v_add_u32_e32 v85, v133, v116
	v_sub_u32_e32 v82, v85, v97
	v_lshl_add_u32 v83, v82, 2, v87
	ds_read_b32 v207, v83 offset:384
	v_add_u32_e32 v84, v133, v117
	v_sub_u32_e32 v85, v84, v97
	v_lshl_add_u32 v82, v85, 2, v87
	ds_read_b32 v208, v82 offset:384
	v_add_u32_e32 v83, v133, v118
	v_sub_u32_e32 v84, v83, v97
	v_lshl_add_u32 v85, v84, 2, v87
	ds_read_b32 v209, v85 offset:384
	v_add_u32_e32 v82, v133, v119
	v_sub_u32_e32 v83, v82, v97
	v_lshl_add_u32 v84, v83, 2, v87
	ds_read_b32 v210, v84 offset:384
	s_waitcnt lgkmcnt(7)
	v_add_u32_e32 v85, v133, v120
	v_sub_u32_e32 v82, v85, v97
	v_lshl_add_u32 v83, v82, 2, v87
	ds_read_b32 v211, v83 offset:384
	v_add_u32_e32 v84, v133, v121
	v_sub_u32_e32 v85, v84, v97
	v_lshl_add_u32 v82, v85, 2, v87
	ds_read_b32 v212, v82 offset:384
	v_add_u32_e32 v83, v133, v122
	v_sub_u32_e32 v84, v83, v97
	v_lshl_add_u32 v85, v84, 2, v87
	ds_read_b32 v213, v85 offset:384
	v_add_u32_e32 v82, v133, v123
	v_sub_u32_e32 v83, v82, v97
	v_lshl_add_u32 v84, v83, 2, v87
	ds_read_b32 v214, v84 offset:384
	v_add_u32_e32 v85, v133, v124
	v_sub_u32_e32 v82, v85, v97
	v_lshl_add_u32 v83, v82, 2, v87
	ds_read_b32 v215, v83 offset:384
	v_add_u32_e32 v84, v133, v125
	v_sub_u32_e32 v85, v84, v97
	v_lshl_add_u32 v82, v85, 2, v87
	ds_read_b32 v216, v82 offset:384
	v_add_u32_e32 v83, v133, v126
	v_sub_u32_e32 v84, v83, v97
	v_lshl_add_u32 v85, v84, 2, v87
	ds_read_b32 v217, v85 offset:384
	v_add_u32_e32 v82, v133, v127
	v_sub_u32_e32 v83, v82, v97
	v_lshl_add_u32 v84, v83, 2, v87
	ds_read_b32 v218, v84 offset:384
	s_waitcnt lgkmcnt(7)
	v_add_u32_e32 v85, v133, v94
	v_sub_u32_e32 v82, v85, v97
	v_lshl_add_u32 v83, v82, 2, v87
	ds_read_b32 v219, v83 offset:512
	v_add_u32_e32 v84, v133, v113
	v_sub_u32_e32 v85, v84, v97
	v_lshl_add_u32 v82, v85, 2, v87
	ds_read_b32 v220, v82 offset:512
	v_add_u32_e32 v83, v133, v114
	v_sub_u32_e32 v84, v83, v97
	v_lshl_add_u32 v85, v84, 2, v87
	ds_read_b32 v221, v85 offset:512
	v_add_u32_e32 v82, v133, v115
	v_sub_u32_e32 v83, v82, v97
	v_lshl_add_u32 v84, v83, 2, v87
	ds_read_b32 v222, v84 offset:512
	v_add_u32_e32 v85, v133, v116
	v_sub_u32_e32 v82, v85, v97
	v_lshl_add_u32 v83, v82, 2, v87
	ds_read_b32 v223, v83 offset:512
	v_add_u32_e32 v84, v133, v117
	v_sub_u32_e32 v85, v84, v97
	v_lshl_add_u32 v82, v85, 2, v87
	ds_read_b32 v226, v82 offset:512
	v_add_u32_e32 v83, v133, v118
	v_sub_u32_e32 v84, v83, v97
	v_lshl_add_u32 v85, v84, 2, v87
	ds_read_b32 v227, v85 offset:512
	v_add_u32_e32 v82, v133, v119
	v_sub_u32_e32 v83, v82, v97
	v_lshl_add_u32 v84, v83, 2, v87
	ds_read_b32 v228, v84 offset:512
	s_waitcnt lgkmcnt(7)
	v_add_u32_e32 v85, v133, v120
	v_sub_u32_e32 v82, v85, v97
	v_lshl_add_u32 v83, v82, 2, v87
	ds_read_b32 v229, v83 offset:512
	v_add_u32_e32 v84, v133, v121
	v_sub_u32_e32 v85, v84, v97
	v_lshl_add_u32 v82, v85, 2, v87
	ds_read_b32 v234, v82 offset:512
	v_add_u32_e32 v83, v133, v122
	v_sub_u32_e32 v84, v83, v97
	v_lshl_add_u32 v85, v84, 2, v87
	ds_read_b32 v235, v85 offset:512
	v_add_u32_e32 v82, v133, v123
	v_sub_u32_e32 v83, v82, v97
	v_lshl_add_u32 v84, v83, 2, v87
	ds_read_b32 v236, v84 offset:512
	v_add_u32_e32 v85, v133, v124
	v_sub_u32_e32 v82, v85, v97
	v_lshl_add_u32 v83, v82, 2, v87
	ds_read_b32 v237, v83 offset:512
	v_add_u32_e32 v84, v133, v125
	v_sub_u32_e32 v85, v84, v97
	v_lshl_add_u32 v82, v85, 2, v87
	ds_read_b32 v244, v82 offset:512
	v_add_u32_e32 v83, v133, v126
	v_sub_u32_e32 v84, v83, v97
	v_lshl_add_u32 v85, v84, 2, v87
	ds_read_b32 v245, v85 offset:512
	v_add_u32_e32 v82, v133, v127
	v_sub_u32_e32 v83, v82, v97
	v_lshl_add_u32 v84, v83, 2, v87
	ds_read_b32 v246, v84 offset:512
	s_waitcnt lgkmcnt(0)
	v_subrev_u32_e32 v82, 64, v133
	v_or_b32_e32 v87, v82, v94
	v_sub_u32_e32 v83, v87, v97
	v_add_u32_e32 v86, 64, v83
	v_cmp_gt_u32_e64 s[2:3], s73, v86
	v_cmp_lt_i32_e64 s[4:5], v87, v134
	s_and_b64 s[2:3], s[4:5], s[2:3]
	v_mul_i32_i24_e32 v85, 0x204, v98
	s_and_b64 s[4:5], vcc, s[2:3]
	v_mov_b32_e32 v83, 0xf149f2ca
	v_mov_b32_e32 v84, 0xf149f2ca
	s_and_saveexec_b64 s[2:3], s[4:5]
	s_cbranch_execz .LBB0_1839
	v_lshl_add_u32 v84, v86, 2, v85
	v_mov_b32_e32 v84, v148
	v_fmac_f32_e32 v84, 0x3e000000, v66
	v_mul_f32_e32 v84, 0x3fb8aa3b, v84
.LBB0_1839:
	s_or_b64 exec, exec, s[2:3]
	v_or_b32_e32 v86, 1, v87
	v_sub_u32_e32 v66, v86, v97
	v_add_u32_e32 v66, 64, v66
	v_cmp_gt_u32_e64 s[2:3], s73, v66
	v_cmp_lt_i32_e64 s[4:5], v86, v134
	s_and_b64 s[2:3], s[4:5], s[2:3]
	s_and_b64 s[4:5], vcc, s[2:3]
	s_and_saveexec_b64 s[2:3], s[4:5]
	s_cbranch_execz .LBB0_1841
	v_lshl_add_u32 v66, v66, 2, v85
	v_mov_b32_e32 v66, v149
	v_fmac_f32_e32 v66, 0x3e000000, v67
	v_mul_f32_e32 v83, 0x3fb8aa3b, v66
.LBB0_1841:
	s_or_b64 exec, exec, s[2:3]
	v_or_b32_e32 v67, 2, v87
	v_sub_u32_e32 v66, v67, v97
	v_add_u32_e32 v66, 64, v66
	v_cmp_gt_u32_e64 s[2:3], s73, v66
	v_cmp_lt_i32_e64 s[4:5], v67, v134
	s_and_b64 s[2:3], s[4:5], s[2:3]
	s_and_b64 s[4:5], vcc, s[2:3]
	v_mov_b32_e32 v67, 0xf149f2ca
	v_mov_b32_e32 v86, 0xf149f2ca
	s_and_saveexec_b64 s[2:3], s[4:5]
	s_cbranch_execz .LBB0_1843
	v_lshl_add_u32 v66, v66, 2, v85
	v_mov_b32_e32 v66, v150
	v_fmac_f32_e32 v66, 0x3e000000, v68
	v_mul_f32_e32 v86, 0x3fb8aa3b, v66
; DI int rowmap(int r, int lh) { return (r & 3) + 8 * (r >> 2) + 4 * lh; }
; DI void phase_mixb(const Prm& p, unsigned char* smem_raw, int S, int lgS, int& base) {
;     ...
;     float mx = -1e30f;
; #pragma unroll
;     for (int tt = 0; tt < 5; ++tt)
; #pragma unroll
;       for (int r = 0; r < 16; ++r) {
;         const int ik = i0 - 64 + 32 * tt + rowmap(r, lh);
;         const int rel = ik - qi;
;         const bool valid = (rel >= -64) && (rel <= 64) && (ik >= 0) && (ik < L);
;         const int bi = min(max(rel + 64, 0), 128);
;         const float s = valid ? (sc[tt][r] * 0.125f + bt[hd * 129 + bi]) * LOG2E : -1e30f;
;         sc[tt][r] = s;
;         mx = fmaxf(mx, s);
;       }
.LBB0_1843:
	s_or_b64 exec, exec, s[2:3]
	v_or_b32_e32 v68, 3, v87
	v_sub_u32_e32 v66, v68, v97
	v_add_u32_e32 v66, 64, v66
	v_cmp_gt_u32_e64 s[2:3], s73, v66
	v_cmp_lt_i32_e64 s[4:5], v68, v134
	s_and_b64 s[2:3], s[4:5], s[2:3]
	s_and_b64 s[4:5], vcc, s[2:3]
	s_and_saveexec_b64 s[2:3], s[4:5]
	s_cbranch_execz .LBB0_1845
	v_lshl_add_u32 v66, v66, 2, v85
	v_mov_b32_e32 v66, v151
	v_fmac_f32_e32 v66, 0x3e000000, v69
	v_mul_f32_e32 v67, 0x3fb8aa3b, v66
.LBB0_1845:
	s_or_b64 exec, exec, s[2:3]
	v_or_b32_e32 v68, 8, v87
	v_sub_u32_e32 v66, v68, v97
	v_add_u32_e32 v66, 64, v66
	v_cmp_gt_u32_e64 s[2:3], s73, v66
	v_cmp_lt_i32_e64 s[4:5], v68, v134
	s_and_b64 s[2:3], s[4:5], s[2:3]
	s_and_b64 s[4:5], vcc, s[2:3]
	v_mov_b32_e32 v68, 0xf149f2ca
	v_mov_b32_e32 v69, 0xf149f2ca
	s_and_saveexec_b64 s[2:3], s[4:5]
	s_cbranch_execz .LBB0_1847
	v_lshl_add_u32 v66, v66, 2, v85
	v_mov_b32_e32 v66, v152
	v_fmac_f32_e32 v66, 0x3e000000, v70
	v_mul_f32_e32 v69, 0x3fb8aa3b, v66
.LBB0_1847:
	s_or_b64 exec, exec, s[2:3]
	v_or_b32_e32 v70, 9, v87
	v_sub_u32_e32 v66, v70, v97
	v_add_u32_e32 v66, 64, v66
	v_cmp_gt_u32_e64 s[2:3], s73, v66
	v_cmp_lt_i32_e64 s[4:5], v70, v134
	s_and_b64 s[2:3], s[4:5], s[2:3]
	s_and_b64 s[4:5], vcc, s[2:3]
	s_and_saveexec_b64 s[2:3], s[4:5]
	s_cbranch_execz .LBB0_1849
	v_lshl_add_u32 v66, v66, 2, v85
	v_mov_b32_e32 v66, v153
	v_fmac_f32_e32 v66, 0x3e000000, v71
	v_mul_f32_e32 v68, 0x3fb8aa3b, v66
.LBB0_1849:
	s_or_b64 exec, exec, s[2:3]
	v_or_b32_e32 v70, 10, v87
	v_sub_u32_e32 v66, v70, v97
	v_add_u32_e32 v66, 64, v66
	v_cmp_gt_u32_e64 s[2:3], s73, v66
	v_cmp_lt_i32_e64 s[4:5], v70, v134
	s_and_b64 s[2:3], s[4:5], s[2:3]
	s_and_b64 s[4:5], vcc, s[2:3]
	v_mov_b32_e32 v70, 0xf149f2ca
	v_mov_b32_e32 v71, 0xf149f2ca
	s_and_saveexec_b64 s[2:3], s[4:5]
	s_cbranch_execz .LBB0_1851
	v_lshl_add_u32 v66, v66, 2, v85
	v_mov_b32_e32 v66, v154
	v_fmac_f32_e32 v66, 0x3e000000, v72
	v_mul_f32_e32 v71, 0x3fb8aa3b, v66
.LBB0_1851:
	s_or_b64 exec, exec, s[2:3]
	v_or_b32_e32 v72, 11, v87
	v_sub_u32_e32 v66, v72, v97
	v_add_u32_e32 v66, 64, v66
	v_cmp_gt_u32_e64 s[2:3], s73, v66
	v_cmp_lt_i32_e64 s[4:5], v72, v134
	s_and_b64 s[2:3], s[4:5], s[2:3]
	s_and_b64 s[4:5], vcc, s[2:3]
	s_and_saveexec_b64 s[2:3], s[4:5]
	s_cbranch_execz .LBB0_1853
	v_lshl_add_u32 v66, v66, 2, v85
	v_mov_b32_e32 v66, v155
	v_fmac_f32_e32 v66, 0x3e000000, v73
	v_mul_f32_e32 v70, 0x3fb8aa3b, v66
.LBB0_1853:
	s_or_b64 exec, exec, s[2:3]
	v_or_b32_e32 v72, 16, v87
	v_sub_u32_e32 v66, v72, v97
	v_add_u32_e32 v66, 64, v66
	v_cmp_gt_u32_e64 s[2:3], s73, v66
	v_cmp_lt_i32_e64 s[4:5], v72, v134
	s_and_b64 s[2:3], s[4:5], s[2:3]
	s_and_b64 s[4:5], vcc, s[2:3]
	v_mov_b32_e32 v72, 0xf149f2ca
	v_mov_b32_e32 v73, 0xf149f2ca
	s_and_saveexec_b64 s[2:3], s[4:5]
	s_cbranch_execz .LBB0_1855
	v_lshl_add_u32 v66, v66, 2, v85
	v_mov_b32_e32 v66, v163
	v_fmac_f32_e32 v66, 0x3e000000, v74
	v_mul_f32_e32 v73, 0x3fb8aa3b, v66
.LBB0_1855:
	s_or_b64 exec, exec, s[2:3]
	v_or_b32_e32 v74, 17, v87
	v_sub_u32_e32 v66, v74, v97
	v_add_u32_e32 v66, 64, v66
	v_cmp_gt_u32_e64 s[2:3], s73, v66
	v_cmp_lt_i32_e64 s[4:5], v74, v134
	s_and_b64 s[2:3], s[4:5], s[2:3]
	s_and_b64 s[4:5], vcc, s[2:3]
	s_and_saveexec_b64 s[2:3], s[4:5]
	s_cbranch_execz .LBB0_1857
	v_lshl_add_u32 v66, v66, 2, v85
	v_mov_b32_e32 v66, v164
	v_fmac_f32_e32 v66, 0x3e000000, v75
	v_mul_f32_e32 v72, 0x3fb8aa3b, v66
.LBB0_1857:
	s_or_b64 exec, exec, s[2:3]
	v_or_b32_e32 v74, 18, v87
	v_sub_u32_e32 v66, v74, v97
	v_add_u32_e32 v66, 64, v66
	v_cmp_gt_u32_e64 s[2:3], s73, v66
	v_cmp_lt_i32_e64 s[4:5], v74, v134
	s_and_b64 s[2:3], s[4:5], s[2:3]
	s_and_b64 s[4:5], vcc, s[2:3]
	v_mov_b32_e32 v74, 0xf149f2ca
	v_mov_b32_e32 v75, 0xf149f2ca
	s_and_saveexec_b64 s[2:3], s[4:5]
	s_cbranch_execz .LBB0_1859
	v_lshl_add_u32 v66, v66, 2, v85
	v_mov_b32_e32 v66, v165
	v_fmac_f32_e32 v66, 0x3e000000, v76
	v_mul_f32_e32 v75, 0x3fb8aa3b, v66
.LBB0_1859:
	s_or_b64 exec, exec, s[2:3]
	v_or_b32_e32 v76, 19, v87
	v_sub_u32_e32 v66, v76, v97
	v_add_u32_e32 v66, 64, v66
	v_cmp_gt_u32_e64 s[2:3], s73, v66
	v_cmp_lt_i32_e64 s[4:5], v76, v134
	s_and_b64 s[2:3], s[4:5], s[2:3]
	s_and_b64 s[4:5], vcc, s[2:3]
	s_and_saveexec_b64 s[2:3], s[4:5]
	s_cbranch_execz .LBB0_1861
	v_lshl_add_u32 v66, v66, 2, v85
	v_mov_b32_e32 v66, v166
	v_fmac_f32_e32 v66, 0x3e000000, v77
	v_mul_f32_e32 v74, 0x3fb8aa3b, v66
.LBB0_1861:
	s_or_b64 exec, exec, s[2:3]
	v_or_b32_e32 v76, 24, v87
	v_sub_u32_e32 v66, v76, v97
	v_add_u32_e32 v66, 64, v66
	v_cmp_gt_u32_e64 s[2:3], s73, v66
	v_cmp_lt_i32_e64 s[4:5], v76, v134
	s_and_b64 s[2:3], s[4:5], s[2:3]
	s_and_b64 s[4:5], vcc, s[2:3]
	v_mov_b32_e32 v76, 0xf149f2ca
	v_mov_b32_e32 v77, 0xf149f2ca
	s_and_saveexec_b64 s[2:3], s[4:5]
	s_cbranch_execz .LBB0_1863
	v_lshl_add_u32 v66, v66, 2, v85
	v_mov_b32_e32 v66, v167
	v_fmac_f32_e32 v66, 0x3e000000, v78
	v_mul_f32_e32 v77, 0x3fb8aa3b, v66
.LBB0_1863:
	s_or_b64 exec, exec, s[2:3]
	v_or_b32_e32 v78, 25, v87
	v_sub_u32_e32 v66, v78, v97
	v_add_u32_e32 v66, 64, v66
	v_cmp_gt_u32_e64 s[2:3], s73, v66
	v_cmp_lt_i32_e64 s[4:5], v78, v134
	s_and_b64 s[2:3], s[4:5], s[2:3]
	s_and_b64 s[4:5], vcc, s[2:3]
	s_and_saveexec_b64 s[2:3], s[4:5]
	s_cbranch_execz .LBB0_1865
	v_lshl_add_u32 v66, v66, 2, v85
	v_mov_b32_e32 v66, v168
	v_fmac_f32_e32 v66, 0x3e000000, v79
	v_mul_f32_e32 v76, 0x3fb8aa3b, v66
.LBB0_1865:
	s_or_b64 exec, exec, s[2:3]
	v_or_b32_e32 v78, 26, v87
	v_sub_u32_e32 v66, v78, v97
	v_add_u32_e32 v66, 64, v66
	v_cmp_gt_u32_e64 s[2:3], s73, v66
	v_cmp_lt_i32_e64 s[4:5], v78, v134
	s_and_b64 s[2:3], s[4:5], s[2:3]
	s_and_b64 s[4:5], vcc, s[2:3]
	v_mov_b32_e32 v78, 0xf149f2ca
	v_mov_b32_e32 v79, 0xf149f2ca
	s_and_saveexec_b64 s[2:3], s[4:5]
	s_cbranch_execz .LBB0_1867
	v_lshl_add_u32 v66, v66, 2, v85
	v_mov_b32_e32 v66, v169
	v_fmac_f32_e32 v66, 0x3e000000, v80
	v_mul_f32_e32 v79, 0x3fb8aa3b, v66
; DI int rowmap(int r, int lh) { return (r & 3) + 8 * (r >> 2) + 4 * lh; }
; DI void phase_mixb(const Prm& p, unsigned char* smem_raw, int S, int lgS, int& base) {
;     ...
;     float mx = -1e30f;
; #pragma unroll
;     for (int tt = 0; tt < 5; ++tt)
; #pragma unroll
;       for (int r = 0; r < 16; ++r) {
;         const int ik = i0 - 64 + 32 * tt + rowmap(r, lh);
;         const int rel = ik - qi;
;         const bool valid = (rel >= -64) && (rel <= 64) && (ik >= 0) && (ik < L);
;         const int bi = min(max(rel + 64, 0), 128);
;         const float s = valid ? (sc[tt][r] * 0.125f + bt[hd * 129 + bi]) * LOG2E : -1e30f;
;         sc[tt][r] = s;
;         mx = fmaxf(mx, s);
;       }
.LBB0_1867:
	s_or_b64 exec, exec, s[2:3]
	v_or_b32_e32 v80, 27, v87
	v_sub_u32_e32 v66, v80, v97
	v_add_u32_e32 v66, 64, v66
	v_cmp_gt_u32_e64 s[2:3], s73, v66
	v_cmp_lt_i32_e64 s[4:5], v80, v134
	s_and_b64 s[2:3], s[4:5], s[2:3]
	s_and_b64 s[4:5], vcc, s[2:3]
	s_and_saveexec_b64 s[2:3], s[4:5]
	s_cbranch_execz .LBB0_1869
	v_lshl_add_u32 v66, v66, 2, v85
	v_mov_b32_e32 v66, v170
	v_fmac_f32_e32 v66, 0x3e000000, v81
	v_mul_f32_e32 v78, 0x3fb8aa3b, v66
.LBB0_1869:
	s_or_b64 exec, exec, s[2:3]
	v_subrev_u32_e32 v66, 32, v133
	v_or_b32_e32 v87, v66, v94
	v_sub_u32_e32 v80, v87, v97
	v_add_u32_e32 v88, 64, v80
	v_cmp_gt_u32_e64 s[2:3], s73, v88
	v_cmp_lt_i32_e64 s[4:5], v87, v134
	v_cmp_ne_u32_e32 vcc, 0, v135
	s_and_b64 s[2:3], s[4:5], s[2:3]
	s_and_b64 s[4:5], vcc, s[2:3]
	v_mov_b32_e32 v80, 0xf149f2ca
	v_mov_b32_e32 v81, 0xf149f2ca
	s_and_saveexec_b64 s[2:3], s[4:5]
	s_cbranch_execz .LBB0_1871
	v_lshl_add_u32 v81, v88, 2, v85
	v_mov_b32_e32 v81, v171
	v_fmac_f32_e32 v81, 0x3e000000, v50
	v_mul_f32_e32 v81, 0x3fb8aa3b, v81
.LBB0_1871:
	s_or_b64 exec, exec, s[2:3]
	v_or_b32_e32 v88, 1, v87
	v_sub_u32_e32 v50, v88, v97
	v_add_u32_e32 v50, 64, v50
	v_cmp_gt_u32_e64 s[2:3], s73, v50
	v_cmp_lt_i32_e64 s[4:5], v88, v134
	s_and_b64 s[2:3], s[4:5], s[2:3]
	s_and_b64 s[4:5], vcc, s[2:3]
	s_and_saveexec_b64 s[2:3], s[4:5]
	s_cbranch_execz .LBB0_1873
	v_lshl_add_u32 v50, v50, 2, v85
	v_mov_b32_e32 v50, v172
	v_fmac_f32_e32 v50, 0x3e000000, v51
	v_mul_f32_e32 v80, 0x3fb8aa3b, v50
.LBB0_1873:
	s_or_b64 exec, exec, s[2:3]
	v_or_b32_e32 v50, 2, v87
	v_sub_u32_e32 v51, v50, v97
	v_add_u32_e32 v88, 64, v51
	v_cmp_gt_u32_e64 s[2:3], s73, v88
	v_cmp_lt_i32_e64 s[4:5], v50, v134
	s_and_b64 s[2:3], s[4:5], s[2:3]
	s_and_b64 s[4:5], vcc, s[2:3]
	v_mov_b32_e32 v50, 0xf149f2ca
	v_mov_b32_e32 v51, 0xf149f2ca
	s_and_saveexec_b64 s[2:3], s[4:5]
	s_cbranch_execz .LBB0_1875
	v_lshl_add_u32 v51, v88, 2, v85
	v_mov_b32_e32 v51, v173
	v_fmac_f32_e32 v51, 0x3e000000, v52
	v_mul_f32_e32 v51, 0x3fb8aa3b, v51
.LBB0_1875:
	s_or_b64 exec, exec, s[2:3]
	v_or_b32_e32 v88, 3, v87
	v_sub_u32_e32 v52, v88, v97
	v_add_u32_e32 v52, 64, v52
	v_cmp_gt_u32_e64 s[2:3], s73, v52
	v_cmp_lt_i32_e64 s[4:5], v88, v134
	s_and_b64 s[2:3], s[4:5], s[2:3]
	s_and_b64 s[4:5], vcc, s[2:3]
	s_and_saveexec_b64 s[2:3], s[4:5]
	s_cbranch_execz .LBB0_1877
	v_lshl_add_u32 v50, v52, 2, v85
	v_mov_b32_e32 v50, v174
	v_fmac_f32_e32 v50, 0x3e000000, v53
	v_mul_f32_e32 v50, 0x3fb8aa3b, v50
.LBB0_1877:
	s_or_b64 exec, exec, s[2:3]
	v_or_b32_e32 v52, 8, v87
	v_sub_u32_e32 v53, v52, v97
	v_add_u32_e32 v88, 64, v53
	v_cmp_gt_u32_e64 s[2:3], s73, v88
	v_cmp_lt_i32_e64 s[4:5], v52, v134
	s_and_b64 s[2:3], s[4:5], s[2:3]
	s_and_b64 s[4:5], vcc, s[2:3]
	v_mov_b32_e32 v52, 0xf149f2ca
	v_mov_b32_e32 v53, 0xf149f2ca
	s_and_saveexec_b64 s[2:3], s[4:5]
	s_cbranch_execz .LBB0_1879
	v_lshl_add_u32 v53, v88, 2, v85
	v_mov_b32_e32 v53, v175
	v_fmac_f32_e32 v53, 0x3e000000, v54
	v_mul_f32_e32 v53, 0x3fb8aa3b, v53
.LBB0_1879:
	s_or_b64 exec, exec, s[2:3]
	v_or_b32_e32 v88, 9, v87
	v_sub_u32_e32 v54, v88, v97
	v_add_u32_e32 v54, 64, v54
	v_cmp_gt_u32_e64 s[2:3], s73, v54
	v_cmp_lt_i32_e64 s[4:5], v88, v134
	s_and_b64 s[2:3], s[4:5], s[2:3]
	s_and_b64 s[4:5], vcc, s[2:3]
	s_and_saveexec_b64 s[2:3], s[4:5]
	s_cbranch_execz .LBB0_1881
	v_lshl_add_u32 v52, v54, 2, v85
	v_mov_b32_e32 v52, v176
	v_fmac_f32_e32 v52, 0x3e000000, v55
	v_mul_f32_e32 v52, 0x3fb8aa3b, v52
.LBB0_1881:
	s_or_b64 exec, exec, s[2:3]
	v_or_b32_e32 v54, 10, v87
	v_sub_u32_e32 v55, v54, v97
	v_add_u32_e32 v88, 64, v55
	v_cmp_gt_u32_e64 s[2:3], s73, v88
	v_cmp_lt_i32_e64 s[4:5], v54, v134
	s_and_b64 s[2:3], s[4:5], s[2:3]
	s_and_b64 s[4:5], vcc, s[2:3]
	v_mov_b32_e32 v54, 0xf149f2ca
	v_mov_b32_e32 v55, 0xf149f2ca
	s_and_saveexec_b64 s[2:3], s[4:5]
	s_cbranch_execz .LBB0_1883
	v_lshl_add_u32 v55, v88, 2, v85
	v_mov_b32_e32 v55, v177
	v_fmac_f32_e32 v55, 0x3e000000, v56
	v_mul_f32_e32 v55, 0x3fb8aa3b, v55
.LBB0_1883:
	s_or_b64 exec, exec, s[2:3]
	v_or_b32_e32 v88, 11, v87
	v_sub_u32_e32 v56, v88, v97
	v_add_u32_e32 v56, 64, v56
	v_cmp_gt_u32_e64 s[2:3], s73, v56
	v_cmp_lt_i32_e64 s[4:5], v88, v134
	s_and_b64 s[2:3], s[4:5], s[2:3]
	s_and_b64 s[4:5], vcc, s[2:3]
	s_and_saveexec_b64 s[2:3], s[4:5]
	s_cbranch_execz .LBB0_1885
	v_lshl_add_u32 v54, v56, 2, v85
	v_mov_b32_e32 v54, v178
	v_fmac_f32_e32 v54, 0x3e000000, v57
	v_mul_f32_e32 v54, 0x3fb8aa3b, v54
.LBB0_1885:
	s_or_b64 exec, exec, s[2:3]
	v_or_b32_e32 v56, 16, v87
	v_sub_u32_e32 v57, v56, v97
	v_add_u32_e32 v88, 64, v57
	v_cmp_gt_u32_e64 s[2:3], s73, v88
	v_cmp_lt_i32_e64 s[4:5], v56, v134
	s_and_b64 s[2:3], s[4:5], s[2:3]
	s_and_b64 s[4:5], vcc, s[2:3]
	v_mov_b32_e32 v56, 0xf149f2ca
	v_mov_b32_e32 v57, 0xf149f2ca
	s_and_saveexec_b64 s[2:3], s[4:5]
	s_cbranch_execz .LBB0_1887
	v_lshl_add_u32 v57, v88, 2, v85
	v_mov_b32_e32 v57, v179
	v_fmac_f32_e32 v57, 0x3e000000, v58
	v_mul_f32_e32 v57, 0x3fb8aa3b, v57
.LBB0_1887:
	s_or_b64 exec, exec, s[2:3]
	v_or_b32_e32 v88, 17, v87
	v_sub_u32_e32 v58, v88, v97
	v_add_u32_e32 v58, 64, v58
	v_cmp_gt_u32_e64 s[2:3], s73, v58
	v_cmp_lt_i32_e64 s[4:5], v88, v134
	s_and_b64 s[2:3], s[4:5], s[2:3]
	s_and_b64 s[4:5], vcc, s[2:3]
	s_and_saveexec_b64 s[2:3], s[4:5]
	s_cbranch_execz .LBB0_1889
	v_lshl_add_u32 v56, v58, 2, v85
	v_mov_b32_e32 v56, v180
	v_fmac_f32_e32 v56, 0x3e000000, v59
	v_mul_f32_e32 v56, 0x3fb8aa3b, v56
.LBB0_1889:
	s_or_b64 exec, exec, s[2:3]
	v_or_b32_e32 v58, 18, v87
	v_sub_u32_e32 v59, v58, v97
	v_add_u32_e32 v88, 64, v59
	v_cmp_gt_u32_e64 s[2:3], s73, v88
	v_cmp_lt_i32_e64 s[4:5], v58, v134
	s_and_b64 s[2:3], s[4:5], s[2:3]
	s_and_b64 s[4:5], vcc, s[2:3]
	v_mov_b32_e32 v58, 0xf149f2ca
	v_mov_b32_e32 v59, 0xf149f2ca
	s_and_saveexec_b64 s[2:3], s[4:5]
	s_cbranch_execz .LBB0_1891
	v_lshl_add_u32 v59, v88, 2, v85
	v_mov_b32_e32 v59, v181
	v_fmac_f32_e32 v59, 0x3e000000, v60
	v_mul_f32_e32 v59, 0x3fb8aa3b, v59
; DI int rowmap(int r, int lh) { return (r & 3) + 8 * (r >> 2) + 4 * lh; }
; DI void phase_mixb(const Prm& p, unsigned char* smem_raw, int S, int lgS, int& base) {
;     ...
;     float mx = -1e30f;
; #pragma unroll
;     for (int tt = 0; tt < 5; ++tt)
; #pragma unroll
;       for (int r = 0; r < 16; ++r) {
;         const int ik = i0 - 64 + 32 * tt + rowmap(r, lh);
;         const int rel = ik - qi;
;         const bool valid = (rel >= -64) && (rel <= 64) && (ik >= 0) && (ik < L);
;         const int bi = min(max(rel + 64, 0), 128);
;         const float s = valid ? (sc[tt][r] * 0.125f + bt[hd * 129 + bi]) * LOG2E : -1e30f;
;         sc[tt][r] = s;
;         mx = fmaxf(mx, s);
;       }
.LBB0_1891:
	s_or_b64 exec, exec, s[2:3]
	v_or_b32_e32 v88, 19, v87
	v_sub_u32_e32 v60, v88, v97
	v_add_u32_e32 v60, 64, v60
	v_cmp_gt_u32_e64 s[2:3], s73, v60
	v_cmp_lt_i32_e64 s[4:5], v88, v134
	s_and_b64 s[2:3], s[4:5], s[2:3]
	s_and_b64 s[4:5], vcc, s[2:3]
	s_and_saveexec_b64 s[2:3], s[4:5]
	s_cbranch_execz .LBB0_1893
	v_lshl_add_u32 v58, v60, 2, v85
	v_mov_b32_e32 v58, v182
	v_fmac_f32_e32 v58, 0x3e000000, v61
	v_mul_f32_e32 v58, 0x3fb8aa3b, v58
.LBB0_1893:
	s_or_b64 exec, exec, s[2:3]
	v_or_b32_e32 v60, 24, v87
	v_sub_u32_e32 v61, v60, v97
	v_add_u32_e32 v88, 64, v61
	v_cmp_gt_u32_e64 s[2:3], s73, v88
	v_cmp_lt_i32_e64 s[4:5], v60, v134
	s_and_b64 s[2:3], s[4:5], s[2:3]
	s_and_b64 s[4:5], vcc, s[2:3]
	v_mov_b32_e32 v60, 0xf149f2ca
	v_mov_b32_e32 v61, 0xf149f2ca
	s_and_saveexec_b64 s[2:3], s[4:5]
	s_cbranch_execz .LBB0_1895
	v_lshl_add_u32 v61, v88, 2, v85
	v_mov_b32_e32 v61, v183
	v_fmac_f32_e32 v61, 0x3e000000, v62
	v_mul_f32_e32 v61, 0x3fb8aa3b, v61
.LBB0_1895:
	s_or_b64 exec, exec, s[2:3]
	v_or_b32_e32 v88, 25, v87
	v_sub_u32_e32 v62, v88, v97
	v_add_u32_e32 v62, 64, v62
	v_cmp_gt_u32_e64 s[2:3], s73, v62
	v_cmp_lt_i32_e64 s[4:5], v88, v134
	s_and_b64 s[2:3], s[4:5], s[2:3]
	s_and_b64 s[4:5], vcc, s[2:3]
	s_and_saveexec_b64 s[2:3], s[4:5]
	s_cbranch_execz .LBB0_1897
	v_lshl_add_u32 v60, v62, 2, v85
	v_mov_b32_e32 v60, v184
	v_fmac_f32_e32 v60, 0x3e000000, v63
	v_mul_f32_e32 v60, 0x3fb8aa3b, v60
.LBB0_1897:
	s_or_b64 exec, exec, s[2:3]
	v_or_b32_e32 v62, 26, v87
	v_sub_u32_e32 v63, v62, v97
	v_add_u32_e32 v88, 64, v63
	v_cmp_gt_u32_e64 s[2:3], s73, v88
	v_cmp_lt_i32_e64 s[4:5], v62, v134
	s_and_b64 s[2:3], s[4:5], s[2:3]
	s_and_b64 s[4:5], vcc, s[2:3]
	v_mov_b32_e32 v62, 0xf149f2ca
	v_mov_b32_e32 v63, 0xf149f2ca
	s_and_saveexec_b64 s[2:3], s[4:5]
	s_cbranch_execz .LBB0_1899
	v_lshl_add_u32 v63, v88, 2, v85
	v_mov_b32_e32 v63, v185
	v_fmac_f32_e32 v63, 0x3e000000, v64
	v_mul_f32_e32 v63, 0x3fb8aa3b, v63
.LBB0_1899:
	s_or_b64 exec, exec, s[2:3]
	v_or_b32_e32 v87, 27, v87
	v_sub_u32_e32 v64, v87, v97
	v_add_u32_e32 v64, 64, v64
	v_cmp_gt_u32_e64 s[2:3], s73, v64
	v_cmp_lt_i32_e64 s[4:5], v87, v134
	s_and_b64 s[2:3], s[4:5], s[2:3]
	s_and_b64 s[4:5], vcc, s[2:3]
	s_and_saveexec_b64 s[2:3], s[4:5]
	s_cbranch_execz .LBB0_1901
	v_lshl_add_u32 v62, v64, 2, v85
	v_mov_b32_e32 v62, v186
	v_fmac_f32_e32 v62, 0x3e000000, v65
	v_mul_f32_e32 v62, 0x3fb8aa3b, v62
.LBB0_1901:
	s_or_b64 exec, exec, s[2:3]
	v_or_b32_e32 v90, v133, v94
	v_cmp_lt_u32_e32 vcc, v90, v134
	v_mov_b32_e32 v64, 0xf149f2ca
	v_mov_b32_e32 v65, 0xf149f2ca
	s_and_saveexec_b64 s[2:3], vcc
	s_cbranch_execz .LBB0_1903
	v_lshl_add_u32 v65, v107, 2, v85
	v_mov_b32_e32 v65, v187
	v_fmac_f32_e32 v65, 0x3e000000, v34
	v_mul_f32_e32 v65, 0x3fb8aa3b, v65
.LBB0_1903:
	s_or_b64 exec, exec, s[2:3]
	v_or_b32_e32 v34, 1, v90
	v_sub_u32_e32 v87, v34, v97
	v_add_u32_e32 v87, 64, v87
	v_cmp_gt_u32_e32 vcc, s73, v87
	v_cmp_lt_u32_e64 s[2:3], v34, v134
	v_sub_u32_e32 v34, v90, v97
	s_and_b64 s[4:5], vcc, s[2:3]
	v_lshl_add_u32 v91, v34, 2, v85
	s_and_saveexec_b64 s[2:3], s[4:5]
	s_cbranch_execz .LBB0_1905
	v_mov_b32_e32 v34, v188
	v_fmac_f32_e32 v34, 0x3e000000, v35
	v_mul_f32_e32 v64, 0x3fb8aa3b, v34
.LBB0_1905:
	s_or_b64 exec, exec, s[2:3]
	v_or_b32_e32 v34, 2, v90
	v_sub_u32_e32 v35, v34, v97
	v_add_u32_e32 v35, 64, v35
	v_cmp_gt_u32_e32 vcc, s73, v35
	v_cmp_lt_u32_e64 s[2:3], v34, v134
	s_and_b64 s[4:5], vcc, s[2:3]
	v_mov_b32_e32 v34, 0xf149f2ca
	v_mov_b32_e32 v35, 0xf149f2ca
	s_and_saveexec_b64 s[2:3], s[4:5]
	s_cbranch_execz .LBB0_1907
	v_mov_b32_e32 v35, v189
	v_fmac_f32_e32 v35, 0x3e000000, v36
	v_mul_f32_e32 v35, 0x3fb8aa3b, v35
.LBB0_1907:
	s_or_b64 exec, exec, s[2:3]
	v_or_b32_e32 v36, 3, v90
	v_sub_u32_e32 v87, v36, v97
	v_add_u32_e32 v87, 64, v87
	v_cmp_gt_u32_e32 vcc, s73, v87
	v_cmp_lt_u32_e64 s[2:3], v36, v134
	s_and_b64 s[4:5], vcc, s[2:3]
	s_and_saveexec_b64 s[2:3], s[4:5]
	s_cbranch_execz .LBB0_1909
	v_mov_b32_e32 v34, v190
	v_fmac_f32_e32 v34, 0x3e000000, v37
	v_mul_f32_e32 v34, 0x3fb8aa3b, v34
.LBB0_1909:
	s_or_b64 exec, exec, s[2:3]
	v_or_b32_e32 v36, 8, v90
	v_sub_u32_e32 v37, v36, v97
	v_add_u32_e32 v37, 64, v37
	v_cmp_gt_u32_e32 vcc, s73, v37
	v_cmp_lt_u32_e64 s[2:3], v36, v134
	s_and_b64 s[4:5], vcc, s[2:3]
	v_mov_b32_e32 v88, 0xf149f2ca
	v_mov_b32_e32 v87, 0xf149f2ca
	s_and_saveexec_b64 s[2:3], s[4:5]
	s_cbranch_execz .LBB0_1911
	v_mov_b32_e32 v36, v191
	v_fmac_f32_e32 v36, 0x3e000000, v38
	v_mul_f32_e32 v87, 0x3fb8aa3b, v36
.LBB0_1911:
	s_or_b64 exec, exec, s[2:3]
	v_or_b32_e32 v36, 9, v90
	v_sub_u32_e32 v37, v36, v97
	v_add_u32_e32 v37, 64, v37
	v_cmp_gt_u32_e32 vcc, s73, v37
	v_cmp_lt_u32_e64 s[2:3], v36, v134
	s_and_b64 s[4:5], vcc, s[2:3]
	s_and_saveexec_b64 s[2:3], s[4:5]
	s_cbranch_execz .LBB0_1913
	v_mov_b32_e32 v36, v192
	v_fmac_f32_e32 v36, 0x3e000000, v39
	v_mul_f32_e32 v88, 0x3fb8aa3b, v36
.LBB0_1913:
	s_or_b64 exec, exec, s[2:3]
	v_or_b32_e32 v36, 10, v90
	v_sub_u32_e32 v37, v36, v97
	v_add_u32_e32 v37, 64, v37
	v_cmp_gt_u32_e32 vcc, s73, v37
	v_cmp_lt_u32_e64 s[2:3], v36, v134
	s_and_b64 s[4:5], vcc, s[2:3]
	v_mov_b32_e32 v39, 0xf149f2ca
	v_mov_b32_e32 v89, 0xf149f2ca
	s_and_saveexec_b64 s[2:3], s[4:5]
	s_cbranch_execz .LBB0_1915
	v_mov_b32_e32 v36, v193
	v_fmac_f32_e32 v36, 0x3e000000, v40
	v_mul_f32_e32 v89, 0x3fb8aa3b, v36
.LBB0_1915:
	s_or_b64 exec, exec, s[2:3]
	v_or_b32_e32 v36, 11, v90
	v_sub_u32_e32 v37, v36, v97
	v_add_u32_e32 v37, 64, v37
	v_cmp_gt_u32_e32 vcc, s73, v37
	v_cmp_lt_u32_e64 s[2:3], v36, v134
	s_and_b64 s[4:5], vcc, s[2:3]
	s_and_saveexec_b64 s[2:3], s[4:5]
	s_cbranch_execz .LBB0_1917
	v_mov_b32_e32 v36, v194
	v_fmac_f32_e32 v36, 0x3e000000, v41
	v_mul_f32_e32 v39, 0x3fb8aa3b, v36
; DI int rowmap(int r, int lh) { return (r & 3) + 8 * (r >> 2) + 4 * lh; }
; DI void phase_mixb(const Prm& p, unsigned char* smem_raw, int S, int lgS, int& base) {
;     ...
;     float mx = -1e30f;
; #pragma unroll
;     for (int tt = 0; tt < 5; ++tt)
; #pragma unroll
;       for (int r = 0; r < 16; ++r) {
;         const int ik = i0 - 64 + 32 * tt + rowmap(r, lh);
;         const int rel = ik - qi;
;         const bool valid = (rel >= -64) && (rel <= 64) && (ik >= 0) && (ik < L);
;         const int bi = min(max(rel + 64, 0), 128);
;         const float s = valid ? (sc[tt][r] * 0.125f + bt[hd * 129 + bi]) * LOG2E : -1e30f;
;         sc[tt][r] = s;
;         mx = fmaxf(mx, s);
;       }
.LBB0_1917:
	s_or_b64 exec, exec, s[2:3]
	v_or_b32_e32 v36, 16, v90
	v_sub_u32_e32 v37, v36, v97
	v_add_u32_e32 v37, 64, v37
	v_cmp_gt_u32_e32 vcc, s73, v37
	v_cmp_lt_u32_e64 s[2:3], v36, v134
	s_and_b64 s[4:5], vcc, s[2:3]
	v_mov_b32_e32 v40, 0xf149f2ca
	v_mov_b32_e32 v41, 0xf149f2ca
	s_and_saveexec_b64 s[2:3], s[4:5]
	s_cbranch_execz .LBB0_1919
	v_mov_b32_e32 v36, v195
	v_fmac_f32_e32 v36, 0x3e000000, v42
	v_mul_f32_e32 v41, 0x3fb8aa3b, v36
.LBB0_1919:
	s_or_b64 exec, exec, s[2:3]
	v_or_b32_e32 v36, 17, v90
	v_sub_u32_e32 v37, v36, v97
	v_add_u32_e32 v37, 64, v37
	v_cmp_gt_u32_e32 vcc, s73, v37
	v_cmp_lt_u32_e64 s[2:3], v36, v134
	s_and_b64 s[4:5], vcc, s[2:3]
	s_and_saveexec_b64 s[2:3], s[4:5]
	s_cbranch_execz .LBB0_1921
	v_mov_b32_e32 v36, v196
	v_fmac_f32_e32 v36, 0x3e000000, v43
	v_mul_f32_e32 v40, 0x3fb8aa3b, v36
.LBB0_1921:
	s_or_b64 exec, exec, s[2:3]
	v_or_b32_e32 v36, 18, v90
	v_sub_u32_e32 v37, v36, v97
	v_add_u32_e32 v37, 64, v37
	v_cmp_gt_u32_e32 vcc, s73, v37
	v_cmp_lt_u32_e64 s[2:3], v36, v134
	s_and_b64 s[4:5], vcc, s[2:3]
	v_mov_b32_e32 v42, 0xf149f2ca
	v_mov_b32_e32 v43, 0xf149f2ca
	s_and_saveexec_b64 s[2:3], s[4:5]
	s_cbranch_execz .LBB0_1923
	v_mov_b32_e32 v36, v197
	v_fmac_f32_e32 v36, 0x3e000000, v44
	v_mul_f32_e32 v43, 0x3fb8aa3b, v36
.LBB0_1923:
	s_or_b64 exec, exec, s[2:3]
	v_or_b32_e32 v36, 19, v90
	v_sub_u32_e32 v37, v36, v97
	v_add_u32_e32 v37, 64, v37
	v_cmp_gt_u32_e32 vcc, s73, v37
	v_cmp_lt_u32_e64 s[2:3], v36, v134
	s_and_b64 s[4:5], vcc, s[2:3]
	s_and_saveexec_b64 s[2:3], s[4:5]
	s_cbranch_execz .LBB0_1925
	v_mov_b32_e32 v36, v198
	v_fmac_f32_e32 v36, 0x3e000000, v45
	v_mul_f32_e32 v42, 0x3fb8aa3b, v36
.LBB0_1925:
	s_or_b64 exec, exec, s[2:3]
	v_or_b32_e32 v36, 24, v90
	v_sub_u32_e32 v37, v36, v97
	v_add_u32_e32 v37, 64, v37
	v_cmp_gt_u32_e32 vcc, s73, v37
	v_cmp_lt_u32_e64 s[2:3], v36, v134
	s_and_b64 s[4:5], vcc, s[2:3]
	v_mov_b32_e32 v44, 0xf149f2ca
	v_mov_b32_e32 v45, 0xf149f2ca
	s_and_saveexec_b64 s[2:3], s[4:5]
	s_cbranch_execz .LBB0_1927
	v_mov_b32_e32 v36, v199
	v_fmac_f32_e32 v36, 0x3e000000, v46
	v_mul_f32_e32 v45, 0x3fb8aa3b, v36
.LBB0_1927:
	s_or_b64 exec, exec, s[2:3]
	v_or_b32_e32 v36, 25, v90
	v_sub_u32_e32 v37, v36, v97
	v_add_u32_e32 v37, 64, v37
	v_cmp_gt_u32_e32 vcc, s73, v37
	v_cmp_lt_u32_e64 s[2:3], v36, v134
	s_and_b64 s[4:5], vcc, s[2:3]
	s_and_saveexec_b64 s[2:3], s[4:5]
	s_cbranch_execz .LBB0_1929
	v_mov_b32_e32 v36, v200
	v_fmac_f32_e32 v36, 0x3e000000, v47
	v_mul_f32_e32 v44, 0x3fb8aa3b, v36
.LBB0_1929:
	s_or_b64 exec, exec, s[2:3]
	v_or_b32_e32 v36, 26, v90
	v_sub_u32_e32 v37, v36, v97
	v_add_u32_e32 v37, 64, v37
	v_cmp_gt_u32_e32 vcc, s73, v37
	v_cmp_lt_u32_e64 s[2:3], v36, v134
	s_and_b64 s[4:5], vcc, s[2:3]
	v_mov_b32_e32 v46, 0xf149f2ca
	v_mov_b32_e32 v47, 0xf149f2ca
	s_and_saveexec_b64 s[2:3], s[4:5]
	s_cbranch_execz .LBB0_1931
	v_mov_b32_e32 v36, v201
	v_fmac_f32_e32 v36, 0x3e000000, v48
	v_mul_f32_e32 v47, 0x3fb8aa3b, v36
.LBB0_1931:
	s_or_b64 exec, exec, s[2:3]
	v_or_b32_e32 v36, 27, v90
	v_sub_u32_e32 v37, v36, v97
	v_add_u32_e32 v37, 64, v37
	v_cmp_gt_u32_e32 vcc, s73, v37
	v_cmp_lt_u32_e64 s[2:3], v36, v134
	s_and_b64 s[4:5], vcc, s[2:3]
	s_and_saveexec_b64 s[2:3], s[4:5]
	s_cbranch_execz .LBB0_1933
	v_mov_b32_e32 v36, v202
	v_fmac_f32_e32 v36, 0x3e000000, v49
	v_mul_f32_e32 v46, 0x3fb8aa3b, v36
.LBB0_1933:
	s_or_b64 exec, exec, s[2:3]
	v_add_u32_e32 v38, 32, v133
	v_or_b32_e32 v37, v38, v94
	v_sub_u32_e32 v36, v37, v97
	v_add_u32_e32 v36, 64, v36
	v_cmp_gt_u32_e32 vcc, s73, v36
	v_cmp_lt_u32_e64 s[2:3], v37, v134
	s_and_b64 s[4:5], vcc, s[2:3]
	v_mov_b32_e32 v48, 0xf149f2ca
	v_add_u32_e32 v36, v133, v94
	v_mov_b32_e32 v49, 0xf149f2ca
	s_and_saveexec_b64 s[2:3], s[4:5]
	s_cbranch_execz .LBB0_1935
	v_sub_u32_e32 v49, v36, v97
	v_lshl_add_u32 v49, v49, 2, v85
	v_mov_b32_e32 v49, v203
	v_fmac_f32_e32 v49, 0x3e000000, v18
	v_mul_f32_e32 v49, 0x3fb8aa3b, v49
.LBB0_1935:
	s_or_b64 exec, exec, s[2:3]
	v_or_b32_e32 v18, 1, v37
	v_sub_u32_e32 v90, v18, v97
	v_add_u32_e32 v90, 64, v90
	v_cmp_gt_u32_e32 vcc, s73, v90
	v_cmp_lt_u32_e64 s[2:3], v18, v134
	v_add_u32_e32 v18, v133, v113
	s_and_b64 s[4:5], vcc, s[2:3]
	v_sub_u32_e32 v90, v18, v97
	s_and_saveexec_b64 s[2:3], s[4:5]
	s_cbranch_execz .LBB0_1937
	v_lshl_add_u32 v18, v90, 2, v85
	v_mov_b32_e32 v18, v204
	v_fmac_f32_e32 v18, 0x3e000000, v19
	v_mul_f32_e32 v48, 0x3fb8aa3b, v18
.LBB0_1937:
	s_or_b64 exec, exec, s[2:3]
	v_or_b32_e32 v18, 2, v37
	v_sub_u32_e32 v19, v18, v97
	v_add_u32_e32 v19, 64, v19
	v_cmp_gt_u32_e32 vcc, s73, v19
	v_cmp_lt_u32_e64 s[2:3], v18, v134
	v_add_u32_e32 v19, v133, v114
	s_and_b64 s[4:5], vcc, s[2:3]
	v_mov_b32_e32 v18, 0xf149f2ca
	v_sub_u32_e32 v92, v19, v97
	v_mov_b32_e32 v19, 0xf149f2ca
	s_and_saveexec_b64 s[2:3], s[4:5]
	s_cbranch_execz .LBB0_1939
	v_lshl_add_u32 v19, v92, 2, v85
	v_mov_b32_e32 v19, v205
	v_fmac_f32_e32 v19, 0x3e000000, v20
	v_mul_f32_e32 v19, 0x3fb8aa3b, v19
.LBB0_1939:
	s_or_b64 exec, exec, s[2:3]
	v_or_b32_e32 v20, 3, v37
	v_sub_u32_e32 v91, v20, v97
	v_add_u32_e32 v91, 64, v91
	v_cmp_gt_u32_e32 vcc, s73, v91
	v_cmp_lt_u32_e64 s[2:3], v20, v134
	v_add_u32_e32 v20, v133, v115
	s_and_b64 s[4:5], vcc, s[2:3]
	v_sub_u32_e32 v93, v20, v97
	s_and_saveexec_b64 s[2:3], s[4:5]
	s_cbranch_execz .LBB0_1941
	v_lshl_add_u32 v18, v93, 2, v85
	v_mov_b32_e32 v18, v206
	v_fmac_f32_e32 v18, 0x3e000000, v21
	v_mul_f32_e32 v18, 0x3fb8aa3b, v18
; DI int rowmap(int r, int lh) { return (r & 3) + 8 * (r >> 2) + 4 * lh; }
; DI void phase_mixb(const Prm& p, unsigned char* smem_raw, int S, int lgS, int& base) {
;     ...
;     float mx = -1e30f;
; #pragma unroll
;     for (int tt = 0; tt < 5; ++tt)
; #pragma unroll
;       for (int r = 0; r < 16; ++r) {
;         const int ik = i0 - 64 + 32 * tt + rowmap(r, lh);
;         const int rel = ik - qi;
;         const bool valid = (rel >= -64) && (rel <= 64) && (ik >= 0) && (ik < L);
;         const int bi = min(max(rel + 64, 0), 128);
;         const float s = valid ? (sc[tt][r] * 0.125f + bt[hd * 129 + bi]) * LOG2E : -1e30f;
;         sc[tt][r] = s;
;         mx = fmaxf(mx, s);
;       }
.LBB0_1941:
	s_or_b64 exec, exec, s[2:3]
	v_or_b32_e32 v20, 8, v37
	v_sub_u32_e32 v21, v20, v97
	v_add_u32_e32 v21, 64, v21
	v_cmp_gt_u32_e32 vcc, s73, v21
	v_cmp_lt_u32_e64 s[2:3], v20, v134
	v_add_u32_e32 v21, v133, v116
	s_and_b64 s[4:5], vcc, s[2:3]
	v_mov_b32_e32 v20, 0xf149f2ca
	v_sub_u32_e32 v135, v21, v97
	v_mov_b32_e32 v21, 0xf149f2ca
	s_and_saveexec_b64 s[2:3], s[4:5]
	s_cbranch_execz .LBB0_1943
	v_lshl_add_u32 v21, v135, 2, v85
	v_mov_b32_e32 v21, v207
	v_fmac_f32_e32 v21, 0x3e000000, v22
	v_mul_f32_e32 v21, 0x3fb8aa3b, v21
.LBB0_1943:
	s_or_b64 exec, exec, s[2:3]
	v_or_b32_e32 v22, 9, v37
	v_sub_u32_e32 v91, v22, v97
	v_add_u32_e32 v91, 64, v91
	v_cmp_gt_u32_e32 vcc, s73, v91
	v_cmp_lt_u32_e64 s[2:3], v22, v134
	v_add_u32_e32 v22, v133, v117
	s_and_b64 s[4:5], vcc, s[2:3]
	v_sub_u32_e32 v136, v22, v97
	s_and_saveexec_b64 s[2:3], s[4:5]
	s_cbranch_execz .LBB0_1945
	v_lshl_add_u32 v20, v136, 2, v85
	v_mov_b32_e32 v20, v208
	v_fmac_f32_e32 v20, 0x3e000000, v23
	v_mul_f32_e32 v20, 0x3fb8aa3b, v20
.LBB0_1945:
	s_or_b64 exec, exec, s[2:3]
	v_or_b32_e32 v22, 10, v37
	v_sub_u32_e32 v23, v22, v97
	v_add_u32_e32 v23, 64, v23
	v_cmp_gt_u32_e32 vcc, s73, v23
	v_cmp_lt_u32_e64 s[2:3], v22, v134
	v_add_u32_e32 v23, v133, v118
	s_and_b64 s[4:5], vcc, s[2:3]
	v_mov_b32_e32 v22, 0xf149f2ca
	v_sub_u32_e32 v137, v23, v97
	v_mov_b32_e32 v23, 0xf149f2ca
	s_and_saveexec_b64 s[2:3], s[4:5]
	s_cbranch_execz .LBB0_1947
	v_lshl_add_u32 v23, v137, 2, v85
	v_mov_b32_e32 v23, v209
	v_fmac_f32_e32 v23, 0x3e000000, v24
	v_mul_f32_e32 v23, 0x3fb8aa3b, v23
.LBB0_1947:
	s_or_b64 exec, exec, s[2:3]
	v_or_b32_e32 v24, 11, v37
	v_sub_u32_e32 v91, v24, v97
	v_add_u32_e32 v91, 64, v91
	v_cmp_gt_u32_e32 vcc, s73, v91
	v_cmp_lt_u32_e64 s[2:3], v24, v134
	v_add_u32_e32 v24, v133, v119
	s_and_b64 s[4:5], vcc, s[2:3]
	v_sub_u32_e32 v138, v24, v97
	s_and_saveexec_b64 s[2:3], s[4:5]
	s_cbranch_execz .LBB0_1949
	v_lshl_add_u32 v22, v138, 2, v85
	v_mov_b32_e32 v22, v210
	v_fmac_f32_e32 v22, 0x3e000000, v25
	v_mul_f32_e32 v22, 0x3fb8aa3b, v22
.LBB0_1949:
	s_or_b64 exec, exec, s[2:3]
	v_or_b32_e32 v24, 16, v37
	v_sub_u32_e32 v25, v24, v97
	v_add_u32_e32 v25, 64, v25
	v_cmp_gt_u32_e32 vcc, s73, v25
	v_cmp_lt_u32_e64 s[2:3], v24, v134
	v_add_u32_e32 v25, v133, v120
	s_and_b64 s[4:5], vcc, s[2:3]
	v_mov_b32_e32 v24, 0xf149f2ca
	v_sub_u32_e32 v139, v25, v97
	v_mov_b32_e32 v25, 0xf149f2ca
	s_and_saveexec_b64 s[2:3], s[4:5]
	s_cbranch_execz .LBB0_1951
	v_lshl_add_u32 v25, v139, 2, v85
	v_mov_b32_e32 v25, v211
	v_fmac_f32_e32 v25, 0x3e000000, v26
	v_mul_f32_e32 v25, 0x3fb8aa3b, v25
.LBB0_1951:
	s_or_b64 exec, exec, s[2:3]
	v_or_b32_e32 v26, 17, v37
	v_sub_u32_e32 v91, v26, v97
	v_add_u32_e32 v91, 64, v91
	v_cmp_gt_u32_e32 vcc, s73, v91
	v_cmp_lt_u32_e64 s[2:3], v26, v134
	v_add_u32_e32 v26, v133, v121
	s_and_b64 s[4:5], vcc, s[2:3]
	v_sub_u32_e32 v140, v26, v97
	s_and_saveexec_b64 s[2:3], s[4:5]
	s_cbranch_execz .LBB0_1953
	v_lshl_add_u32 v24, v140, 2, v85
	v_mov_b32_e32 v24, v212
	v_fmac_f32_e32 v24, 0x3e000000, v27
	v_mul_f32_e32 v24, 0x3fb8aa3b, v24
.LBB0_1953:
	s_or_b64 exec, exec, s[2:3]
	v_or_b32_e32 v26, 18, v37
	v_sub_u32_e32 v27, v26, v97
	v_add_u32_e32 v27, 64, v27
	v_cmp_gt_u32_e32 vcc, s73, v27
	v_cmp_lt_u32_e64 s[2:3], v26, v134
	v_add_u32_e32 v27, v133, v122
	s_and_b64 s[4:5], vcc, s[2:3]
	v_mov_b32_e32 v26, 0xf149f2ca
	v_sub_u32_e32 v141, v27, v97
	v_mov_b32_e32 v27, 0xf149f2ca
	s_and_saveexec_b64 s[2:3], s[4:5]
	s_cbranch_execz .LBB0_1955
	v_lshl_add_u32 v27, v141, 2, v85
	v_mov_b32_e32 v27, v213
	v_fmac_f32_e32 v27, 0x3e000000, v28
	v_mul_f32_e32 v27, 0x3fb8aa3b, v27
.LBB0_1955:
	s_or_b64 exec, exec, s[2:3]
	v_or_b32_e32 v28, 19, v37
	v_sub_u32_e32 v91, v28, v97
	v_add_u32_e32 v91, 64, v91
	v_cmp_gt_u32_e32 vcc, s73, v91
	v_cmp_lt_u32_e64 s[2:3], v28, v134
	v_add_u32_e32 v28, v133, v123
	s_and_b64 s[4:5], vcc, s[2:3]
	v_sub_u32_e32 v142, v28, v97
	s_and_saveexec_b64 s[2:3], s[4:5]
	s_cbranch_execz .LBB0_1957
	v_lshl_add_u32 v26, v142, 2, v85
	v_mov_b32_e32 v26, v214
	v_fmac_f32_e32 v26, 0x3e000000, v29
	v_mul_f32_e32 v26, 0x3fb8aa3b, v26
.LBB0_1957:
	s_or_b64 exec, exec, s[2:3]
	v_or_b32_e32 v28, 24, v37
	v_sub_u32_e32 v29, v28, v97
	v_add_u32_e32 v29, 64, v29
	v_cmp_gt_u32_e32 vcc, s73, v29
	v_cmp_lt_u32_e64 s[2:3], v28, v134
	v_add_u32_e32 v29, v133, v124
	s_and_b64 s[4:5], vcc, s[2:3]
	v_mov_b32_e32 v28, 0xf149f2ca
	v_sub_u32_e32 v143, v29, v97
	v_mov_b32_e32 v29, 0xf149f2ca
	s_and_saveexec_b64 s[2:3], s[4:5]
	s_cbranch_execz .LBB0_1959
	v_lshl_add_u32 v29, v143, 2, v85
	v_mov_b32_e32 v29, v215
	v_fmac_f32_e32 v29, 0x3e000000, v30
	v_mul_f32_e32 v29, 0x3fb8aa3b, v29
.LBB0_1959:
	s_or_b64 exec, exec, s[2:3]
	v_or_b32_e32 v30, 25, v37
	v_sub_u32_e32 v91, v30, v97
	v_add_u32_e32 v91, 64, v91
	v_cmp_gt_u32_e32 vcc, s73, v91
	v_cmp_lt_u32_e64 s[2:3], v30, v134
	v_add_u32_e32 v30, v133, v125
	s_and_b64 s[4:5], vcc, s[2:3]
	v_sub_u32_e32 v144, v30, v97
	s_and_saveexec_b64 s[2:3], s[4:5]
	s_cbranch_execz .LBB0_1961
	v_lshl_add_u32 v28, v144, 2, v85
	v_mov_b32_e32 v28, v216
	v_fmac_f32_e32 v28, 0x3e000000, v31
	v_mul_f32_e32 v28, 0x3fb8aa3b, v28
.LBB0_1961:
	s_or_b64 exec, exec, s[2:3]
	v_or_b32_e32 v30, 26, v37
	v_sub_u32_e32 v31, v30, v97
	v_add_u32_e32 v31, 64, v31
	v_cmp_gt_u32_e32 vcc, s73, v31
	v_cmp_lt_u32_e64 s[2:3], v30, v134
	v_add_u32_e32 v31, v133, v126
	s_and_b64 s[4:5], vcc, s[2:3]
	v_mov_b32_e32 v30, 0xf149f2ca
	v_sub_u32_e32 v145, v31, v97
	v_mov_b32_e32 v31, 0xf149f2ca
	s_and_saveexec_b64 s[2:3], s[4:5]
	s_cbranch_execz .LBB0_1963
	v_lshl_add_u32 v31, v145, 2, v85
	v_mov_b32_e32 v31, v217
	v_fmac_f32_e32 v31, 0x3e000000, v32
	v_mul_f32_e32 v31, 0x3fb8aa3b, v31
; DI int rowmap(int r, int lh) { return (r & 3) + 8 * (r >> 2) + 4 * lh; }
; DI void phase_mixb(const Prm& p, unsigned char* smem_raw, int S, int lgS, int& base) {
;     ...
;     float mx = -1e30f;
; #pragma unroll
;     for (int tt = 0; tt < 5; ++tt)
; #pragma unroll
;       for (int r = 0; r < 16; ++r) {
;         const int ik = i0 - 64 + 32 * tt + rowmap(r, lh);
;         const int rel = ik - qi;
;         const bool valid = (rel >= -64) && (rel <= 64) && (ik >= 0) && (ik < L);
;         const int bi = min(max(rel + 64, 0), 128);
;         const float s = valid ? (sc[tt][r] * 0.125f + bt[hd * 129 + bi]) * LOG2E : -1e30f;
;         sc[tt][r] = s;
;         mx = fmaxf(mx, s);
;       }
.LBB0_1963:
	s_or_b64 exec, exec, s[2:3]
	v_or_b32_e32 v32, 27, v37
	v_sub_u32_e32 v37, v32, v97
	v_add_u32_e32 v37, 64, v37
	v_cmp_gt_u32_e32 vcc, s73, v37
	v_cmp_lt_u32_e64 s[2:3], v32, v134
	v_add_u32_e32 v32, v133, v127
	s_and_b64 s[4:5], vcc, s[2:3]
	v_sub_u32_e32 v146, v32, v97
	s_and_saveexec_b64 s[2:3], s[4:5]
	s_cbranch_execz .LBB0_1965
	v_lshl_add_u32 v30, v146, 2, v85
	v_mov_b32_e32 v30, v218
	v_fmac_f32_e32 v30, 0x3e000000, v33
	v_mul_f32_e32 v30, 0x3fb8aa3b, v30
.LBB0_1965:
	s_or_b64 exec, exec, s[2:3]
	v_add_u32_e32 v37, 64, v133
	v_or_b32_e32 v147, v37, v94
	v_sub_u32_e32 v32, v147, v97
	v_add_u32_e32 v32, 64, v32
	v_cmp_gt_u32_e32 vcc, s73, v32
	v_cmp_lt_u32_e64 s[2:3], v147, v134
	s_and_b64 s[4:5], vcc, s[2:3]
	v_mov_b32_e32 v32, 0xf149f2ca
	v_mov_b32_e32 v33, 0xf149f2ca
	s_and_saveexec_b64 s[2:3], s[4:5]
	s_cbranch_execz .LBB0_1967
	v_sub_u32_e32 v33, v36, v97
	v_lshl_add_u32 v33, v33, 2, v85
	v_mov_b32_e32 v33, v219
	v_fmac_f32_e32 v33, 0x3e000000, v2
	v_mul_f32_e32 v33, 0x3fb8aa3b, v33
.LBB0_1967:
	s_or_b64 exec, exec, s[2:3]
	v_or_b32_e32 v2, 1, v147
	v_sub_u32_e32 v36, v2, v97
	v_add_u32_e32 v36, 64, v36
	v_cmp_gt_u32_e32 vcc, s73, v36
	v_cmp_lt_u32_e64 s[2:3], v2, v134
	s_and_b64 s[4:5], vcc, s[2:3]
	s_and_saveexec_b64 s[2:3], s[4:5]
	s_cbranch_execz .LBB0_1969
	v_lshl_add_u32 v2, v90, 2, v85
	v_mov_b32_e32 v2, v220
	v_fmac_f32_e32 v2, 0x3e000000, v3
	v_mul_f32_e32 v32, 0x3fb8aa3b, v2
.LBB0_1969:
	s_or_b64 exec, exec, s[2:3]
	v_or_b32_e32 v2, 2, v147
	v_sub_u32_e32 v3, v2, v97
	v_add_u32_e32 v3, 64, v3
	v_cmp_gt_u32_e32 vcc, s73, v3
	v_cmp_lt_u32_e64 s[2:3], v2, v134
	s_and_b64 s[4:5], vcc, s[2:3]
	v_mov_b32_e32 v91, 0xf149f2ca
	v_mov_b32_e32 v156, 0xf149f2ca
	s_and_saveexec_b64 s[2:3], s[4:5]
	s_cbranch_execz .LBB0_1971
	v_lshl_add_u32 v2, v92, 2, v85
	v_mov_b32_e32 v2, v221
	v_fmac_f32_e32 v2, 0x3e000000, v4
	v_mul_f32_e32 v156, 0x3fb8aa3b, v2
.LBB0_1971:
	s_or_b64 exec, exec, s[2:3]
	v_or_b32_e32 v2, 3, v147
	v_sub_u32_e32 v3, v2, v97
	v_add_u32_e32 v3, 64, v3
	v_cmp_gt_u32_e32 vcc, s73, v3
	v_cmp_lt_u32_e64 s[2:3], v2, v134
	s_and_b64 s[4:5], vcc, s[2:3]
	s_and_saveexec_b64 s[2:3], s[4:5]
	s_cbranch_execz .LBB0_1973
	v_lshl_add_u32 v2, v93, 2, v85
	v_mov_b32_e32 v2, v222
	v_fmac_f32_e32 v2, 0x3e000000, v5
	v_mul_f32_e32 v91, 0x3fb8aa3b, v2
.LBB0_1973:
	s_or_b64 exec, exec, s[2:3]
	v_or_b32_e32 v2, 8, v147
	v_sub_u32_e32 v3, v2, v97
	v_add_u32_e32 v3, 64, v3
	v_cmp_gt_u32_e32 vcc, s73, v3
	v_cmp_lt_u32_e64 s[2:3], v2, v134
	s_and_b64 s[4:5], vcc, s[2:3]
	v_mov_b32_e32 v157, 0xf149f2ca
	v_mov_b32_e32 v158, 0xf149f2ca
	s_and_saveexec_b64 s[2:3], s[4:5]
	s_cbranch_execz .LBB0_1975
	v_lshl_add_u32 v2, v135, 2, v85
	v_mov_b32_e32 v2, v223
	v_fmac_f32_e32 v2, 0x3e000000, v6
	v_mul_f32_e32 v158, 0x3fb8aa3b, v2
.LBB0_1975:
	s_or_b64 exec, exec, s[2:3]
	v_or_b32_e32 v2, 9, v147
	v_sub_u32_e32 v3, v2, v97
	v_add_u32_e32 v3, 64, v3
	v_cmp_gt_u32_e32 vcc, s73, v3
	v_cmp_lt_u32_e64 s[2:3], v2, v134
	s_and_b64 s[4:5], vcc, s[2:3]
	s_and_saveexec_b64 s[2:3], s[4:5]
	s_cbranch_execz .LBB0_1977
	v_lshl_add_u32 v2, v136, 2, v85
	v_mov_b32_e32 v2, v226
	v_fmac_f32_e32 v2, 0x3e000000, v7
	v_mul_f32_e32 v157, 0x3fb8aa3b, v2
.LBB0_1977:
	s_or_b64 exec, exec, s[2:3]
	v_or_b32_e32 v2, 10, v147
	v_sub_u32_e32 v3, v2, v97
	v_add_u32_e32 v3, 64, v3
	v_cmp_gt_u32_e32 vcc, s73, v3
	v_cmp_lt_u32_e64 s[2:3], v2, v134
	s_and_b64 s[4:5], vcc, s[2:3]
	v_mov_b32_e32 v159, 0xf149f2ca
	v_mov_b32_e32 v160, 0xf149f2ca
	s_and_saveexec_b64 s[2:3], s[4:5]
	s_cbranch_execz .LBB0_1979
	v_lshl_add_u32 v2, v137, 2, v85
	v_mov_b32_e32 v2, v227
	v_fmac_f32_e32 v2, 0x3e000000, v8
	v_mul_f32_e32 v160, 0x3fb8aa3b, v2
; DI int rowmap(int r, int lh) { return (r & 3) + 8 * (r >> 2) + 4 * lh; }
; DI void phase_mixb(const Prm& p, unsigned char* smem_raw, int S, int lgS, int& base) {
;     ...
;     float mx = -1e30f;
; #pragma unroll
;     for (int tt = 0; tt < 5; ++tt)
; #pragma unroll
;       for (int r = 0; r < 16; ++r) {
;         const int ik = i0 - 64 + 32 * tt + rowmap(r, lh);
;         const int rel = ik - qi;
;         const bool valid = (rel >= -64) && (rel <= 64) && (ik >= 0) && (ik < L);
;         const int bi = min(max(rel + 64, 0), 128);
;         const float s = valid ? (sc[tt][r] * 0.125f + bt[hd * 129 + bi]) * LOG2E : -1e30f;
;         sc[tt][r] = s;
;         mx = fmaxf(mx, s);
;       }
.LBB0_1979:
	s_or_b64 exec, exec, s[2:3]
	v_or_b32_e32 v2, 11, v147
	v_sub_u32_e32 v3, v2, v97
	v_add_u32_e32 v3, 64, v3
	v_cmp_gt_u32_e32 vcc, s73, v3
	v_cmp_lt_u32_e64 s[2:3], v2, v134
	s_and_b64 s[4:5], vcc, s[2:3]
	s_and_saveexec_b64 s[2:3], s[4:5]
	s_cbranch_execz .LBB0_1981
	v_lshl_add_u32 v2, v138, 2, v85
	v_mov_b32_e32 v2, v228
	v_fmac_f32_e32 v2, 0x3e000000, v9
	v_mul_f32_e32 v159, 0x3fb8aa3b, v2
.LBB0_1981:
	s_or_b64 exec, exec, s[2:3]
	v_or_b32_e32 v2, 16, v147
	v_sub_u32_e32 v3, v2, v97
	v_add_u32_e32 v3, 64, v3
	v_cmp_gt_u32_e32 vcc, s73, v3
	v_cmp_lt_u32_e64 s[2:3], v2, v134
	s_and_b64 s[4:5], vcc, s[2:3]
	v_mov_b32_e32 v161, 0xf149f2ca
	v_mov_b32_e32 v162, 0xf149f2ca
	s_and_saveexec_b64 s[2:3], s[4:5]
	s_cbranch_execz .LBB0_1983
	v_lshl_add_u32 v2, v139, 2, v85
	v_mov_b32_e32 v2, v229
	v_fmac_f32_e32 v2, 0x3e000000, v10
	v_mul_f32_e32 v162, 0x3fb8aa3b, v2
.LBB0_1983:
	s_or_b64 exec, exec, s[2:3]
	v_or_b32_e32 v2, 17, v147
	v_sub_u32_e32 v3, v2, v97
	v_add_u32_e32 v3, 64, v3
	v_cmp_gt_u32_e32 vcc, s73, v3
	v_cmp_lt_u32_e64 s[2:3], v2, v134
	s_and_b64 s[4:5], vcc, s[2:3]
	s_and_saveexec_b64 s[2:3], s[4:5]
	s_cbranch_execz .LBB0_1985
	v_lshl_add_u32 v2, v140, 2, v85
	v_mov_b32_e32 v2, v234
	v_fmac_f32_e32 v2, 0x3e000000, v11
	v_mul_f32_e32 v161, 0x3fb8aa3b, v2
.LBB0_1985:
	s_or_b64 exec, exec, s[2:3]
	v_or_b32_e32 v2, 18, v147
	v_sub_u32_e32 v3, v2, v97
	v_add_u32_e32 v3, 64, v3
	v_cmp_gt_u32_e32 vcc, s73, v3
	v_cmp_lt_u32_e64 s[2:3], v2, v134
	s_and_b64 s[4:5], vcc, s[2:3]
	v_mov_b32_e32 v10, 0xf149f2ca
	v_mov_b32_e32 v11, 0xf149f2ca
	s_and_saveexec_b64 s[2:3], s[4:5]
	s_cbranch_execz .LBB0_1987
	v_lshl_add_u32 v2, v141, 2, v85
	v_mov_b32_e32 v2, v235
	v_fmac_f32_e32 v2, 0x3e000000, v12
	v_mul_f32_e32 v11, 0x3fb8aa3b, v2
.LBB0_1987:
	s_or_b64 exec, exec, s[2:3]
	v_or_b32_e32 v2, 19, v147
	v_sub_u32_e32 v3, v2, v97
	v_add_u32_e32 v3, 64, v3
	v_cmp_gt_u32_e32 vcc, s73, v3
	v_cmp_lt_u32_e64 s[2:3], v2, v134
	s_and_b64 s[4:5], vcc, s[2:3]
	s_and_saveexec_b64 s[2:3], s[4:5]
	s_cbranch_execz .LBB0_1989
	v_lshl_add_u32 v2, v142, 2, v85
	v_mov_b32_e32 v2, v236
	v_fmac_f32_e32 v2, 0x3e000000, v13
	v_mul_f32_e32 v10, 0x3fb8aa3b, v2
.LBB0_1989:
	s_or_b64 exec, exec, s[2:3]
	v_or_b32_e32 v2, 24, v147
	v_sub_u32_e32 v3, v2, v97
	v_add_u32_e32 v3, 64, v3
	v_cmp_gt_u32_e32 vcc, s73, v3
	v_cmp_lt_u32_e64 s[2:3], v2, v134
	s_and_b64 s[4:5], vcc, s[2:3]
	v_mov_b32_e32 v12, 0xf149f2ca
	v_mov_b32_e32 v13, 0xf149f2ca
	s_and_saveexec_b64 s[2:3], s[4:5]
	s_cbranch_execz .LBB0_1991
	v_lshl_add_u32 v2, v143, 2, v85
	v_mov_b32_e32 v2, v237
	v_fmac_f32_e32 v2, 0x3e000000, v14
	v_mul_f32_e32 v13, 0x3fb8aa3b, v2
.LBB0_1991:
	s_or_b64 exec, exec, s[2:3]
	v_or_b32_e32 v2, 25, v147
	v_sub_u32_e32 v3, v2, v97
	v_add_u32_e32 v3, 64, v3
	v_cmp_gt_u32_e32 vcc, s73, v3
	v_cmp_lt_u32_e64 s[2:3], v2, v134
	s_and_b64 s[4:5], vcc, s[2:3]
	s_and_saveexec_b64 s[2:3], s[4:5]
	s_cbranch_execz .LBB0_1993
	v_lshl_add_u32 v2, v144, 2, v85
	v_mov_b32_e32 v2, v244
	v_fmac_f32_e32 v2, 0x3e000000, v15
	v_mul_f32_e32 v12, 0x3fb8aa3b, v2
.LBB0_1993:
	s_or_b64 exec, exec, s[2:3]
	v_or_b32_e32 v2, 26, v147
	v_sub_u32_e32 v3, v2, v97
	v_add_u32_e32 v3, 64, v3
	v_cmp_gt_u32_e32 vcc, s73, v3
	v_cmp_lt_u32_e64 s[2:3], v2, v134
	s_and_b64 s[4:5], vcc, s[2:3]
	v_mov_b32_e32 v14, 0xf149f2ca
	v_mov_b32_e32 v15, 0xf149f2ca
	s_and_saveexec_b64 s[2:3], s[4:5]
	s_cbranch_execz .LBB0_1995
	v_lshl_add_u32 v2, v145, 2, v85
	v_mov_b32_e32 v2, v245
	v_fmac_f32_e32 v2, 0x3e000000, v16
	v_mul_f32_e32 v15, 0x3fb8aa3b, v2
.LBB0_1995:
	s_or_b64 exec, exec, s[2:3]
	v_or_b32_e32 v2, 27, v147
	v_sub_u32_e32 v3, v2, v97
	v_add_u32_e32 v3, 64, v3
	v_cmp_gt_u32_e32 vcc, s73, v3
	v_cmp_lt_u32_e64 s[2:3], v2, v134
	s_and_b64 s[4:5], vcc, s[2:3]
	s_and_saveexec_b64 s[2:3], s[4:5]
	s_cbranch_execz .LBB0_1997
	v_lshl_add_u32 v2, v146, 2, v85
	v_mov_b32_e32 v2, v246
	v_fmac_f32_e32 v2, 0x3e000000, v17
	v_mul_f32_e32 v14, 0x3fb8aa3b, v2
